# GEMM K-loops: per-phase s_setprio toggles removed in 8 loops (A/B on top of v7)
# baseline (speedup 1.0000x reference)
.LBB0_284:
	ds_read_b128 v[128:131], v173
	ds_read_b128 v[132:135], v173 offset:1024
	ds_read_b128 v[152:155], v173 offset:2048
	ds_read_b128 v[158:161], v173 offset:3072
	ds_read_b128 v[164:167], v177
	ds_read_b128 v[180:183], v177 offset:1024
	ds_read_b128 v[186:189], v177 offset:2048
	ds_read_b128 v[190:193], v177 offset:3072
	s_add_u32 s30, s4, 0xfffc0080
	s_addc_u32 s31, s5, -1
	s_cmp_eq_u32 s82, 12
	s_cselect_b32 s35, s25, s31
	s_cselect_b32 s34, s73, s30
	s_cselect_b32 s31, s23, s81
	s_cselect_b32 s30, s74, s75
	v_lshl_add_u64 v[170:171], s[4:5], 0, v[146:147]
	s_add_i32 m0, s43, 0xc000
	ds_read_b128 v[194:197], v179
	ds_read_b128 v[198:201], v179 offset:1024
	ds_read_b128 v[202:205], v179 offset:2048
	ds_read_b128 v[206:209], v179 offset:3072
	ds_read_b128 v[210:213], v179 offset:4096
	ds_read_b128 v[214:217], v179 offset:5120
	ds_read_b128 v[218:221], v179 offset:6144
	ds_read_b128 v[222:225], v179 offset:7168
	global_load_lds_dwordx4 v[170:171], off
	v_lshl_add_u64 v[170:171], s[4:5], 0, v[144:145]
	s_add_i32 m0, s43, 0xe000
	s_nop 0
	global_load_lds_dwordx4 v[170:171], off
	s_waitcnt lgkmcnt(0)
	v_mfma_f32_16x16x32_bf16 v[124:127], v[128:131], v[194:197], v[124:127]
	s_waitcnt vmcnt(8)
	s_waitcnt lgkmcnt(0)
	s_barrier
	v_mfma_f32_16x16x32_bf16 v[116:119], v[152:155], v[194:197], v[116:119]
	v_mfma_f32_16x16x32_bf16 v[108:111], v[128:131], v[202:205], v[108:111]
	v_mfma_f32_16x16x32_bf16 v[100:103], v[152:155], v[202:205], v[100:103]
	v_mfma_f32_16x16x32_bf16 v[92:95], v[128:131], v[210:213], v[92:95]
	v_mfma_f32_16x16x32_bf16 v[84:87], v[152:155], v[210:213], v[84:87]
	v_mfma_f32_16x16x32_bf16 v[76:79], v[128:131], v[218:221], v[76:79]
	v_mfma_f32_16x16x32_bf16 v[68:71], v[152:155], v[218:221], v[68:71]
	v_mfma_f32_16x16x32_bf16 v[120:123], v[164:167], v[194:197], v[120:123]
	v_mfma_f32_16x16x32_bf16 v[112:115], v[186:189], v[194:197], v[112:115]
	v_mfma_f32_16x16x32_bf16 v[104:107], v[164:167], v[202:205], v[104:107]
	v_mfma_f32_16x16x32_bf16 v[96:99], v[186:189], v[202:205], v[96:99]
	v_mfma_f32_16x16x32_bf16 v[88:91], v[164:167], v[210:213], v[88:91]
	v_mfma_f32_16x16x32_bf16 v[80:83], v[186:189], v[210:213], v[80:83]
	v_mfma_f32_16x16x32_bf16 v[72:75], v[164:167], v[218:221], v[72:75]
	v_mfma_f32_16x16x32_bf16 v[64:67], v[186:189], v[218:221], v[64:67]
	v_mfma_f32_16x16x32_bf16 v[124:127], v[132:135], v[198:201], v[124:127]
	v_mfma_f32_16x16x32_bf16 v[116:119], v[158:161], v[198:201], v[116:119]
	v_mfma_f32_16x16x32_bf16 v[108:111], v[132:135], v[206:209], v[108:111]
	v_mfma_f32_16x16x32_bf16 v[100:103], v[158:161], v[206:209], v[100:103]
	v_mfma_f32_16x16x32_bf16 v[92:95], v[132:135], v[214:217], v[92:95]
	v_mfma_f32_16x16x32_bf16 v[84:87], v[158:161], v[214:217], v[84:87]
	v_mfma_f32_16x16x32_bf16 v[76:79], v[132:135], v[222:225], v[76:79]
	v_mfma_f32_16x16x32_bf16 v[68:71], v[158:161], v[222:225], v[68:71]
	v_mfma_f32_16x16x32_bf16 v[120:123], v[180:183], v[198:201], v[120:123]
	v_mfma_f32_16x16x32_bf16 v[112:115], v[190:193], v[198:201], v[112:115]
	v_mfma_f32_16x16x32_bf16 v[104:107], v[180:183], v[206:209], v[104:107]
	v_mfma_f32_16x16x32_bf16 v[96:99], v[190:193], v[206:209], v[96:99]
	v_mfma_f32_16x16x32_bf16 v[88:91], v[180:183], v[214:217], v[88:91]
	v_mfma_f32_16x16x32_bf16 v[80:83], v[190:193], v[214:217], v[80:83]
	v_mfma_f32_16x16x32_bf16 v[72:75], v[180:183], v[222:225], v[72:75]
	v_mfma_f32_16x16x32_bf16 v[64:67], v[190:193], v[222:225], v[64:67]
	s_barrier
	s_add_i32 s83, s65, s40
	v_lshl_add_u64 v[170:171], s[30:31], 0, v[140:141]
	s_mov_b32 m0, s83
	ds_read_b128 v[194:197], v179 offset:16384
	ds_read_b128 v[198:201], v179 offset:17408
	ds_read_b128 v[202:205], v179 offset:18432
	ds_read_b128 v[206:209], v179 offset:19456
	ds_read_b128 v[210:213], v179 offset:20480
	ds_read_b128 v[214:217], v179 offset:21504
	ds_read_b128 v[218:221], v179 offset:22528
	ds_read_b128 v[222:225], v179 offset:23552
	global_load_lds_dwordx4 v[170:171], off
	s_add_i32 m0, s83, 0x2000
	s_add_u32 s84, s30, 0x40000
	v_lshl_add_u64 v[174:175], s[30:31], 0, v[136:137]
	s_addc_u32 s85, s31, 0
	s_add_i32 s83, s66, s40
	global_load_lds_dwordx4 v[174:175], off
	v_lshl_add_u64 v[226:227], s[84:85], 0, v[140:141]
	s_mov_b32 m0, s83
	v_lshl_add_u64 v[230:231], s[34:35], 0, v[138:139]
	global_load_lds_dwordx4 v[226:227], off
	v_lshl_add_u64 v[226:227], s[84:85], 0, v[136:137]
	s_add_i32 m0, s83, 0x2000
	s_nop 0
	global_load_lds_dwordx4 v[226:227], off
	v_lshl_add_u64 v[226:227], s[34:35], 0, v[142:143]
	s_mov_b32 m0, s43
	s_nop 0
	global_load_lds_dwordx4 v[226:227], off
	s_mov_b32 m0, s44
	s_nop 0
	global_load_lds_dwordx4 v[230:231], off
	s_waitcnt lgkmcnt(0)
	v_mfma_f32_16x16x32_bf16 v[60:63], v[128:131], v[194:197], v[60:63]
	s_waitcnt vmcnt(8)
	s_waitcnt lgkmcnt(0)
	s_barrier
	v_mfma_f32_16x16x32_bf16 v[52:55], v[152:155], v[194:197], v[52:55]
	v_mfma_f32_16x16x32_bf16 v[44:47], v[128:131], v[202:205], v[44:47]
	v_mfma_f32_16x16x32_bf16 v[36:39], v[152:155], v[202:205], v[36:39]
	v_mfma_f32_16x16x32_bf16 v[28:31], v[128:131], v[210:213], v[28:31]
	v_mfma_f32_16x16x32_bf16 v[20:23], v[152:155], v[210:213], v[20:23]
	v_mfma_f32_16x16x32_bf16 v[12:15], v[128:131], v[218:221], v[12:15]
	v_mfma_f32_16x16x32_bf16 v[4:7], v[152:155], v[218:221], v[4:7]
	v_mfma_f32_16x16x32_bf16 v[56:59], v[164:167], v[194:197], v[56:59]
	v_mfma_f32_16x16x32_bf16 v[48:51], v[186:189], v[194:197], v[48:51]
	v_mfma_f32_16x16x32_bf16 v[40:43], v[164:167], v[202:205], v[40:43]
	v_mfma_f32_16x16x32_bf16 v[32:35], v[186:189], v[202:205], v[32:35]
	v_mfma_f32_16x16x32_bf16 v[24:27], v[164:167], v[210:213], v[24:27]
	v_mfma_f32_16x16x32_bf16 v[16:19], v[186:189], v[210:213], v[16:19]
	v_mfma_f32_16x16x32_bf16 v[8:11], v[164:167], v[218:221], v[8:11]
	v_mfma_f32_16x16x32_bf16 v[0:3], v[186:189], v[218:221], v[0:3]
	v_mfma_f32_16x16x32_bf16 v[60:63], v[132:135], v[198:201], v[60:63]
	v_mfma_f32_16x16x32_bf16 v[52:55], v[158:161], v[198:201], v[52:55]
	v_mfma_f32_16x16x32_bf16 v[44:47], v[132:135], v[206:209], v[44:47]
	v_mfma_f32_16x16x32_bf16 v[36:39], v[158:161], v[206:209], v[36:39]
	v_mfma_f32_16x16x32_bf16 v[28:31], v[132:135], v[214:217], v[28:31]
	v_mfma_f32_16x16x32_bf16 v[20:23], v[158:161], v[214:217], v[20:23]
	v_mfma_f32_16x16x32_bf16 v[12:15], v[132:135], v[222:225], v[12:15]
	v_mfma_f32_16x16x32_bf16 v[4:7], v[158:161], v[222:225], v[4:7]
	v_mfma_f32_16x16x32_bf16 v[56:59], v[180:183], v[198:201], v[56:59]
	v_mfma_f32_16x16x32_bf16 v[48:51], v[190:193], v[198:201], v[48:51]
	v_mfma_f32_16x16x32_bf16 v[40:43], v[180:183], v[206:209], v[40:43]
	v_mfma_f32_16x16x32_bf16 v[32:35], v[190:193], v[206:209], v[32:35]
	v_mfma_f32_16x16x32_bf16 v[24:27], v[180:183], v[214:217], v[24:27]
	v_mfma_f32_16x16x32_bf16 v[16:19], v[190:193], v[214:217], v[16:19]
	v_mfma_f32_16x16x32_bf16 v[8:11], v[180:183], v[222:225], v[8:11]
	v_mfma_f32_16x16x32_bf16 v[0:3], v[190:193], v[222:225], v[0:3]
	s_barrier
	s_add_i32 s83, 0, 0x18000
	v_add_u32_e32 v156, s83, v169
	s_add_i32 s84, 0, 0x1c000
	ds_read_b128 v[128:131], v156
	ds_read_b128 v[132:135], v156 offset:1024
	ds_read_b128 v[152:155], v156 offset:2048
	ds_read_b128 v[158:161], v156 offset:3072
	v_add_u32_e32 v156, s84, v169
	ds_read_b128 v[164:167], v156
	ds_read_b128 v[180:183], v156 offset:1024
	ds_read_b128 v[186:189], v156 offset:2048
	ds_read_b128 v[190:193], v156 offset:3072
	s_add_u32 s34, s34, 0x40000
	s_addc_u32 s35, s35, 0
	s_mov_b32 m0, s45
	v_lshl_add_u64 v[232:233], s[34:35], 0, v[142:143]
	ds_read_b128 v[194:197], v179 offset:32768
	ds_read_b128 v[198:201], v179 offset:33792
	ds_read_b128 v[202:205], v179 offset:34816
	ds_read_b128 v[206:209], v179 offset:35840
	ds_read_b128 v[210:213], v179 offset:36864
	ds_read_b128 v[214:217], v179 offset:37888
	ds_read_b128 v[218:221], v179 offset:38912
	ds_read_b128 v[222:225], v179 offset:39936
	global_load_lds_dwordx4 v[232:233], off
	v_lshl_add_u64 v[232:233], s[34:35], 0, v[138:139]
	s_mov_b32 m0, s55
	s_nop 0
	global_load_lds_dwordx4 v[232:233], off
	s_waitcnt lgkmcnt(0)
	v_mfma_f32_16x16x32_bf16 v[124:127], v[128:131], v[194:197], v[124:127]
	s_waitcnt vmcnt(8)
	s_waitcnt lgkmcnt(0)
	s_barrier
	v_mfma_f32_16x16x32_bf16 v[116:119], v[152:155], v[194:197], v[116:119]
	v_mfma_f32_16x16x32_bf16 v[108:111], v[128:131], v[202:205], v[108:111]
	v_mfma_f32_16x16x32_bf16 v[100:103], v[152:155], v[202:205], v[100:103]
	v_mfma_f32_16x16x32_bf16 v[92:95], v[128:131], v[210:213], v[92:95]
	v_mfma_f32_16x16x32_bf16 v[84:87], v[152:155], v[210:213], v[84:87]
	v_mfma_f32_16x16x32_bf16 v[76:79], v[128:131], v[218:221], v[76:79]
	v_mfma_f32_16x16x32_bf16 v[68:71], v[152:155], v[218:221], v[68:71]
	v_mfma_f32_16x16x32_bf16 v[120:123], v[164:167], v[194:197], v[120:123]
	v_mfma_f32_16x16x32_bf16 v[112:115], v[186:189], v[194:197], v[112:115]
	v_mfma_f32_16x16x32_bf16 v[104:107], v[164:167], v[202:205], v[104:107]
	v_mfma_f32_16x16x32_bf16 v[96:99], v[186:189], v[202:205], v[96:99]
	v_mfma_f32_16x16x32_bf16 v[88:91], v[164:167], v[210:213], v[88:91]
	v_mfma_f32_16x16x32_bf16 v[80:83], v[186:189], v[210:213], v[80:83]
	v_mfma_f32_16x16x32_bf16 v[72:75], v[164:167], v[218:221], v[72:75]
	v_mfma_f32_16x16x32_bf16 v[64:67], v[186:189], v[218:221], v[64:67]
	v_mfma_f32_16x16x32_bf16 v[124:127], v[132:135], v[198:201], v[124:127]
	v_mfma_f32_16x16x32_bf16 v[116:119], v[158:161], v[198:201], v[116:119]
	v_mfma_f32_16x16x32_bf16 v[108:111], v[132:135], v[206:209], v[108:111]
	v_mfma_f32_16x16x32_bf16 v[100:103], v[158:161], v[206:209], v[100:103]
	v_mfma_f32_16x16x32_bf16 v[92:95], v[132:135], v[214:217], v[92:95]
	v_mfma_f32_16x16x32_bf16 v[84:87], v[158:161], v[214:217], v[84:87]
	v_mfma_f32_16x16x32_bf16 v[76:79], v[132:135], v[222:225], v[76:79]
	v_mfma_f32_16x16x32_bf16 v[68:71], v[158:161], v[222:225], v[68:71]
	v_mfma_f32_16x16x32_bf16 v[120:123], v[180:183], v[198:201], v[120:123]
	v_mfma_f32_16x16x32_bf16 v[112:115], v[190:193], v[198:201], v[112:115]
	v_mfma_f32_16x16x32_bf16 v[104:107], v[180:183], v[206:209], v[104:107]
	v_mfma_f32_16x16x32_bf16 v[96:99], v[190:193], v[206:209], v[96:99]
	v_mfma_f32_16x16x32_bf16 v[88:91], v[180:183], v[214:217], v[88:91]
	v_mfma_f32_16x16x32_bf16 v[80:83], v[190:193], v[214:217], v[80:83]
	v_mfma_f32_16x16x32_bf16 v[72:75], v[180:183], v[222:225], v[72:75]
	v_mfma_f32_16x16x32_bf16 v[64:67], v[190:193], v[222:225], v[64:67]
	s_barrier
	s_add_i32 s34, s83, s40
	v_lshl_add_u64 v[170:171], v[170:171], 0, s[12:13]
	s_mov_b32 m0, s34
	ds_read_b128 v[194:197], v179 offset:49152
	ds_read_b128 v[198:201], v179 offset:50176
	ds_read_b128 v[202:205], v179 offset:51200
	ds_read_b128 v[206:209], v179 offset:52224
	ds_read_b128 v[210:213], v179 offset:53248
	ds_read_b128 v[214:217], v179 offset:54272
	ds_read_b128 v[218:221], v179 offset:55296
	ds_read_b128 v[222:225], v179 offset:56320
	global_load_lds_dwordx4 v[170:171], off
	s_add_i32 m0, s34, 0x2000
	s_add_u32 s30, s30, 0x40080
	v_lshl_add_u64 v[170:171], v[174:175], 0, s[12:13]
	s_addc_u32 s31, s31, 0
	s_add_i32 s34, s84, s40
	global_load_lds_dwordx4 v[170:171], off
	v_lshl_add_u64 v[170:171], s[30:31], 0, v[140:141]
	s_mov_b32 m0, s34
	s_nop 0
	global_load_lds_dwordx4 v[170:171], off
	v_lshl_add_u64 v[170:171], s[30:31], 0, v[136:137]
	s_add_i32 m0, s34, 0x2000
	s_nop 0
	global_load_lds_dwordx4 v[170:171], off
	v_lshl_add_u64 v[170:171], v[226:227], 0, s[12:13]
	s_mov_b32 m0, s62
	s_nop 0
	global_load_lds_dwordx4 v[170:171], off
	v_lshl_add_u64 v[170:171], v[230:231], 0, s[12:13]
	s_mov_b32 m0, s63
	s_nop 0
	global_load_lds_dwordx4 v[170:171], off
	s_waitcnt lgkmcnt(0)
	v_mfma_f32_16x16x32_bf16 v[60:63], v[128:131], v[194:197], v[60:63]
	s_waitcnt vmcnt(8)
	s_waitcnt lgkmcnt(0)
	s_barrier
	v_mfma_f32_16x16x32_bf16 v[52:55], v[152:155], v[194:197], v[52:55]
	v_mfma_f32_16x16x32_bf16 v[44:47], v[128:131], v[202:205], v[44:47]
	v_mfma_f32_16x16x32_bf16 v[36:39], v[152:155], v[202:205], v[36:39]
	v_mfma_f32_16x16x32_bf16 v[28:31], v[128:131], v[210:213], v[28:31]
	v_mfma_f32_16x16x32_bf16 v[20:23], v[152:155], v[210:213], v[20:23]
	v_mfma_f32_16x16x32_bf16 v[12:15], v[128:131], v[218:221], v[12:15]
	v_mfma_f32_16x16x32_bf16 v[4:7], v[152:155], v[218:221], v[4:7]
	v_mfma_f32_16x16x32_bf16 v[56:59], v[164:167], v[194:197], v[56:59]
	v_mfma_f32_16x16x32_bf16 v[48:51], v[186:189], v[194:197], v[48:51]
	v_mfma_f32_16x16x32_bf16 v[40:43], v[164:167], v[202:205], v[40:43]
	v_mfma_f32_16x16x32_bf16 v[32:35], v[186:189], v[202:205], v[32:35]
	v_mfma_f32_16x16x32_bf16 v[24:27], v[164:167], v[210:213], v[24:27]
	v_mfma_f32_16x16x32_bf16 v[16:19], v[186:189], v[210:213], v[16:19]
	v_mfma_f32_16x16x32_bf16 v[8:11], v[164:167], v[218:221], v[8:11]
	v_mfma_f32_16x16x32_bf16 v[0:3], v[186:189], v[218:221], v[0:3]
	v_mfma_f32_16x16x32_bf16 v[60:63], v[132:135], v[198:201], v[60:63]
	v_mfma_f32_16x16x32_bf16 v[52:55], v[158:161], v[198:201], v[52:55]
	v_mfma_f32_16x16x32_bf16 v[44:47], v[132:135], v[206:209], v[44:47]
	v_mfma_f32_16x16x32_bf16 v[36:39], v[158:161], v[206:209], v[36:39]
	v_mfma_f32_16x16x32_bf16 v[28:31], v[132:135], v[214:217], v[28:31]
	v_mfma_f32_16x16x32_bf16 v[20:23], v[158:161], v[214:217], v[20:23]
	v_mfma_f32_16x16x32_bf16 v[12:15], v[132:135], v[222:225], v[12:15]
	v_mfma_f32_16x16x32_bf16 v[4:7], v[158:161], v[222:225], v[4:7]
	v_mfma_f32_16x16x32_bf16 v[56:59], v[180:183], v[198:201], v[56:59]
	v_mfma_f32_16x16x32_bf16 v[48:51], v[190:193], v[198:201], v[48:51]
	v_mfma_f32_16x16x32_bf16 v[40:43], v[180:183], v[206:209], v[40:43]
	v_mfma_f32_16x16x32_bf16 v[32:35], v[190:193], v[206:209], v[32:35]
	v_mfma_f32_16x16x32_bf16 v[24:27], v[180:183], v[214:217], v[24:27]
	v_mfma_f32_16x16x32_bf16 v[16:19], v[190:193], v[214:217], v[16:19]
	v_mfma_f32_16x16x32_bf16 v[8:11], v[180:183], v[222:225], v[8:11]
	v_mfma_f32_16x16x32_bf16 v[0:3], v[190:193], v[222:225], v[0:3]
	s_barrier
	s_add_i32 s82, s82, 2
	s_add_u32 s75, s75, 0x100
	s_addc_u32 s81, s81, 0
	s_add_u32 s4, s4, 0x100
	s_addc_u32 s5, s5, 0
	s_cmp_gt_u32 s82, 13
	s_cbranch_scc0 .LBB0_284
	s_and_b64 vcc, exec, s[14:15]
	s_cbranch_vccz .LBB0_287
	s_barrier

.LBB0_358:
	ds_read_b128 v[96:99], v233
	ds_read_b128 v[100:103], v233 offset:1024
	ds_read_b128 v[152:155], v233 offset:2048
	ds_read_b128 v[156:159], v233 offset:3072
	ds_read_b128 v[160:163], v234
	ds_read_b128 v[164:167], v234 offset:1024
	ds_read_b128 v[168:171], v234 offset:2048
	ds_read_b128 v[172:175], v234 offset:3072
	s_add_u32 s20, s18, 0x100
	s_addc_u32 s21, s19, 0
	s_cmp_eq_u32 s73, 40
	s_cselect_b32 s25, s5, s21
	s_cselect_b32 s24, s4, s20
	s_cselect_b32 s23, s17, s72
	s_cselect_b32 s22, s16, s67
	v_lshl_add_u64 v[208:209], s[18:19], 0, v[146:147]
	s_add_i32 m0, s31, 0xc000
	ds_read_b128 v[176:179], v235
	ds_read_b128 v[180:183], v235 offset:1024
	ds_read_b128 v[184:187], v235 offset:2048
	ds_read_b128 v[188:191], v235 offset:3072
	ds_read_b128 v[192:195], v235 offset:4096
	ds_read_b128 v[196:199], v235 offset:5120
	ds_read_b128 v[200:203], v235 offset:6144
	ds_read_b128 v[204:207], v235 offset:7168
	global_load_lds_dwordx4 v[208:209], off
	v_lshl_add_u64 v[208:209], s[18:19], 0, v[144:145]
	s_add_i32 m0, s31, 0xe000
	s_nop 0
	global_load_lds_dwordx4 v[208:209], off
	s_waitcnt lgkmcnt(0)
	v_mfma_f32_16x16x32_bf16 v[132:135], v[96:99], v[176:179], v[132:135]
	s_waitcnt vmcnt(8)
	s_waitcnt lgkmcnt(0)
	s_barrier
	v_mfma_f32_16x16x32_bf16 v[128:131], v[152:155], v[176:179], v[128:131]
	v_mfma_f32_16x16x32_bf16 v[124:127], v[96:99], v[184:187], v[124:127]
	v_mfma_f32_16x16x32_bf16 v[120:123], v[152:155], v[184:187], v[120:123]
	v_mfma_f32_16x16x32_bf16 v[116:119], v[96:99], v[192:195], v[116:119]
	v_mfma_f32_16x16x32_bf16 v[112:115], v[152:155], v[192:195], v[112:115]
	v_mfma_f32_16x16x32_bf16 v[108:111], v[96:99], v[200:203], v[108:111]
	v_mfma_f32_16x16x32_bf16 v[104:107], v[152:155], v[200:203], v[104:107]
	v_mfma_f32_16x16x32_bf16 v[60:63], v[160:163], v[176:179], v[60:63]
	v_mfma_f32_16x16x32_bf16 v[56:59], v[168:171], v[176:179], v[56:59]
	v_mfma_f32_16x16x32_bf16 v[52:55], v[160:163], v[184:187], v[52:55]
	v_mfma_f32_16x16x32_bf16 v[48:51], v[168:171], v[184:187], v[48:51]
	v_mfma_f32_16x16x32_bf16 v[44:47], v[160:163], v[192:195], v[44:47]
	v_mfma_f32_16x16x32_bf16 v[40:43], v[168:171], v[192:195], v[40:43]
	v_mfma_f32_16x16x32_bf16 v[36:39], v[160:163], v[200:203], v[36:39]
	v_mfma_f32_16x16x32_bf16 v[32:35], v[168:171], v[200:203], v[32:35]
	v_mfma_f32_16x16x32_bf16 v[132:135], v[100:103], v[180:183], v[132:135]
	v_mfma_f32_16x16x32_bf16 v[128:131], v[156:159], v[180:183], v[128:131]
	v_mfma_f32_16x16x32_bf16 v[124:127], v[100:103], v[188:191], v[124:127]
	v_mfma_f32_16x16x32_bf16 v[120:123], v[156:159], v[188:191], v[120:123]
	v_mfma_f32_16x16x32_bf16 v[116:119], v[100:103], v[196:199], v[116:119]
	v_mfma_f32_16x16x32_bf16 v[112:115], v[156:159], v[196:199], v[112:115]
	v_mfma_f32_16x16x32_bf16 v[108:111], v[100:103], v[204:207], v[108:111]
	v_mfma_f32_16x16x32_bf16 v[104:107], v[156:159], v[204:207], v[104:107]
	v_mfma_f32_16x16x32_bf16 v[60:63], v[164:167], v[180:183], v[60:63]
	v_mfma_f32_16x16x32_bf16 v[56:59], v[172:175], v[180:183], v[56:59]
	v_mfma_f32_16x16x32_bf16 v[52:55], v[164:167], v[188:191], v[52:55]
	v_mfma_f32_16x16x32_bf16 v[48:51], v[172:175], v[188:191], v[48:51]
	v_mfma_f32_16x16x32_bf16 v[44:47], v[164:167], v[196:199], v[44:47]
	v_mfma_f32_16x16x32_bf16 v[40:43], v[172:175], v[196:199], v[40:43]
	v_mfma_f32_16x16x32_bf16 v[36:39], v[164:167], v[204:207], v[36:39]
	v_mfma_f32_16x16x32_bf16 v[32:35], v[172:175], v[204:207], v[32:35]
	s_barrier
	s_add_i32 s18, s61, s30
	v_lshl_add_u64 v[208:209], s[22:23], 0, v[138:139]
	s_mov_b32 m0, s18
	ds_read_b128 v[176:179], v235 offset:16384
	ds_read_b128 v[180:183], v235 offset:17408
	ds_read_b128 v[184:187], v235 offset:18432
	ds_read_b128 v[188:191], v235 offset:19456
	ds_read_b128 v[192:195], v235 offset:20480
	ds_read_b128 v[196:199], v235 offset:21504
	ds_read_b128 v[200:203], v235 offset:22528
	ds_read_b128 v[204:207], v235 offset:23552
	global_load_lds_dwordx4 v[208:209], off
	s_add_i32 m0, s18, 0x2000
	s_add_u32 s18, s22, 0xb0000
	v_lshl_add_u64 v[210:211], s[22:23], 0, v[142:143]
	s_addc_u32 s19, s23, 0
	s_add_i32 s74, s62, s30
	global_load_lds_dwordx4 v[210:211], off
	v_lshl_add_u64 v[212:213], s[18:19], 0, v[138:139]
	s_mov_b32 m0, s74
	v_lshl_add_u64 v[214:215], s[24:25], 0, v[140:141]
	global_load_lds_dwordx4 v[212:213], off
	v_lshl_add_u64 v[212:213], s[18:19], 0, v[142:143]
	s_add_i32 m0, s74, 0x2000
	s_nop 0
	global_load_lds_dwordx4 v[212:213], off
	v_lshl_add_u64 v[212:213], s[24:25], 0, v[136:137]
	s_mov_b32 m0, s31
	s_nop 0
	global_load_lds_dwordx4 v[212:213], off
	s_mov_b32 m0, s34
	s_nop 0
	global_load_lds_dwordx4 v[214:215], off
	s_waitcnt lgkmcnt(0)
	v_mfma_f32_16x16x32_bf16 v[92:95], v[96:99], v[176:179], v[92:95]
	s_waitcnt vmcnt(8)
	s_waitcnt lgkmcnt(0)
	s_barrier
	v_mfma_f32_16x16x32_bf16 v[88:91], v[152:155], v[176:179], v[88:91]
	v_mfma_f32_16x16x32_bf16 v[84:87], v[96:99], v[184:187], v[84:87]
	v_mfma_f32_16x16x32_bf16 v[80:83], v[152:155], v[184:187], v[80:83]
	v_mfma_f32_16x16x32_bf16 v[76:79], v[96:99], v[192:195], v[76:79]
	v_mfma_f32_16x16x32_bf16 v[72:75], v[152:155], v[192:195], v[72:75]
	v_mfma_f32_16x16x32_bf16 v[68:71], v[96:99], v[200:203], v[68:71]
	v_mfma_f32_16x16x32_bf16 v[64:67], v[152:155], v[200:203], v[64:67]
	v_mfma_f32_16x16x32_bf16 v[28:31], v[160:163], v[176:179], v[28:31]
	v_mfma_f32_16x16x32_bf16 v[24:27], v[168:171], v[176:179], v[24:27]
	v_mfma_f32_16x16x32_bf16 v[20:23], v[160:163], v[184:187], v[20:23]
	v_mfma_f32_16x16x32_bf16 v[16:19], v[168:171], v[184:187], v[16:19]
	v_mfma_f32_16x16x32_bf16 v[12:15], v[160:163], v[192:195], v[12:15]
	v_mfma_f32_16x16x32_bf16 v[8:11], v[168:171], v[192:195], v[8:11]
	v_mfma_f32_16x16x32_bf16 v[4:7], v[160:163], v[200:203], v[4:7]
	v_mfma_f32_16x16x32_bf16 v[0:3], v[168:171], v[200:203], v[0:3]
	v_mfma_f32_16x16x32_bf16 v[92:95], v[100:103], v[180:183], v[92:95]
	v_mfma_f32_16x16x32_bf16 v[88:91], v[156:159], v[180:183], v[88:91]
	v_mfma_f32_16x16x32_bf16 v[84:87], v[100:103], v[188:191], v[84:87]
	v_mfma_f32_16x16x32_bf16 v[80:83], v[156:159], v[188:191], v[80:83]
	v_mfma_f32_16x16x32_bf16 v[76:79], v[100:103], v[196:199], v[76:79]
	v_mfma_f32_16x16x32_bf16 v[72:75], v[156:159], v[196:199], v[72:75]
	v_mfma_f32_16x16x32_bf16 v[68:71], v[100:103], v[204:207], v[68:71]
	v_mfma_f32_16x16x32_bf16 v[64:67], v[156:159], v[204:207], v[64:67]
	v_mfma_f32_16x16x32_bf16 v[28:31], v[164:167], v[180:183], v[28:31]
	v_mfma_f32_16x16x32_bf16 v[24:27], v[172:175], v[180:183], v[24:27]
	v_mfma_f32_16x16x32_bf16 v[20:23], v[164:167], v[188:191], v[20:23]
	v_mfma_f32_16x16x32_bf16 v[16:19], v[172:175], v[188:191], v[16:19]
	v_mfma_f32_16x16x32_bf16 v[12:15], v[164:167], v[196:199], v[12:15]
	v_mfma_f32_16x16x32_bf16 v[8:11], v[172:175], v[196:199], v[8:11]
	v_mfma_f32_16x16x32_bf16 v[4:7], v[164:167], v[204:207], v[4:7]
	v_mfma_f32_16x16x32_bf16 v[0:3], v[172:175], v[204:207], v[0:3]
	s_barrier
	s_add_i32 s74, 0, 0x18000
	s_add_i32 s75, 0, 0x1c000
	v_add_u32_e32 v156, s74, v232
	v_add_u32_e32 v172, s75, v232
	ds_read_b128 v[96:99], v156
	ds_read_b128 v[100:103], v156 offset:1024
	ds_read_b128 v[152:155], v156 offset:2048
	ds_read_b128 v[156:159], v156 offset:3072
	ds_read_b128 v[160:163], v172
	ds_read_b128 v[164:167], v172 offset:1024
	ds_read_b128 v[168:171], v172 offset:2048
	ds_read_b128 v[172:175], v172 offset:3072
	s_add_u32 s18, s24, 0xb0000
	s_addc_u32 s19, s25, 0
	s_mov_b32 m0, s35
	v_lshl_add_u64 v[216:217], s[18:19], 0, v[136:137]
	ds_read_b128 v[176:179], v235 offset:32768
	ds_read_b128 v[180:183], v235 offset:33792
	ds_read_b128 v[184:187], v235 offset:34816
	ds_read_b128 v[188:191], v235 offset:35840
	ds_read_b128 v[192:195], v235 offset:36864
	ds_read_b128 v[196:199], v235 offset:37888
	ds_read_b128 v[200:203], v235 offset:38912
	ds_read_b128 v[204:207], v235 offset:39936
	global_load_lds_dwordx4 v[216:217], off
	v_lshl_add_u64 v[216:217], s[18:19], 0, v[140:141]
	s_mov_b32 m0, s38
	s_nop 0
	global_load_lds_dwordx4 v[216:217], off
	s_waitcnt lgkmcnt(0)
	v_mfma_f32_16x16x32_bf16 v[132:135], v[96:99], v[176:179], v[132:135]
	s_waitcnt vmcnt(8)
	s_waitcnt lgkmcnt(0)
	s_barrier
	v_mfma_f32_16x16x32_bf16 v[128:131], v[152:155], v[176:179], v[128:131]
	v_mfma_f32_16x16x32_bf16 v[124:127], v[96:99], v[184:187], v[124:127]
	v_mfma_f32_16x16x32_bf16 v[120:123], v[152:155], v[184:187], v[120:123]
	v_mfma_f32_16x16x32_bf16 v[116:119], v[96:99], v[192:195], v[116:119]
	v_mfma_f32_16x16x32_bf16 v[112:115], v[152:155], v[192:195], v[112:115]
	v_mfma_f32_16x16x32_bf16 v[108:111], v[96:99], v[200:203], v[108:111]
	v_mfma_f32_16x16x32_bf16 v[104:107], v[152:155], v[200:203], v[104:107]
	v_mfma_f32_16x16x32_bf16 v[60:63], v[160:163], v[176:179], v[60:63]
	v_mfma_f32_16x16x32_bf16 v[56:59], v[168:171], v[176:179], v[56:59]
	v_mfma_f32_16x16x32_bf16 v[52:55], v[160:163], v[184:187], v[52:55]
	v_mfma_f32_16x16x32_bf16 v[48:51], v[168:171], v[184:187], v[48:51]
	v_mfma_f32_16x16x32_bf16 v[44:47], v[160:163], v[192:195], v[44:47]
	v_mfma_f32_16x16x32_bf16 v[40:43], v[168:171], v[192:195], v[40:43]
	v_mfma_f32_16x16x32_bf16 v[36:39], v[160:163], v[200:203], v[36:39]
	v_mfma_f32_16x16x32_bf16 v[32:35], v[168:171], v[200:203], v[32:35]
	v_mfma_f32_16x16x32_bf16 v[132:135], v[100:103], v[180:183], v[132:135]
	v_mfma_f32_16x16x32_bf16 v[128:131], v[156:159], v[180:183], v[128:131]
	v_mfma_f32_16x16x32_bf16 v[124:127], v[100:103], v[188:191], v[124:127]
	v_mfma_f32_16x16x32_bf16 v[120:123], v[156:159], v[188:191], v[120:123]
	v_mfma_f32_16x16x32_bf16 v[116:119], v[100:103], v[196:199], v[116:119]
	v_mfma_f32_16x16x32_bf16 v[112:115], v[156:159], v[196:199], v[112:115]
	v_mfma_f32_16x16x32_bf16 v[108:111], v[100:103], v[204:207], v[108:111]
	v_mfma_f32_16x16x32_bf16 v[104:107], v[156:159], v[204:207], v[104:107]
	v_mfma_f32_16x16x32_bf16 v[60:63], v[164:167], v[180:183], v[60:63]
	v_mfma_f32_16x16x32_bf16 v[56:59], v[172:175], v[180:183], v[56:59]
	v_mfma_f32_16x16x32_bf16 v[52:55], v[164:167], v[188:191], v[52:55]
	v_mfma_f32_16x16x32_bf16 v[48:51], v[172:175], v[188:191], v[48:51]
	v_mfma_f32_16x16x32_bf16 v[44:47], v[164:167], v[196:199], v[44:47]
	v_mfma_f32_16x16x32_bf16 v[40:43], v[172:175], v[196:199], v[40:43]
	v_mfma_f32_16x16x32_bf16 v[36:39], v[164:167], v[204:207], v[36:39]
	v_mfma_f32_16x16x32_bf16 v[32:35], v[172:175], v[204:207], v[32:35]
	s_barrier
	s_add_i32 s18, s74, s30
	v_lshl_add_u64 v[208:209], v[208:209], 0, s[12:13]
	s_mov_b32 m0, s18
	ds_read_b128 v[176:179], v235 offset:49152
	ds_read_b128 v[180:183], v235 offset:50176
	ds_read_b128 v[184:187], v235 offset:51200
	ds_read_b128 v[188:191], v235 offset:52224
	ds_read_b128 v[192:195], v235 offset:53248
	ds_read_b128 v[196:199], v235 offset:54272
	ds_read_b128 v[200:203], v235 offset:55296
	ds_read_b128 v[204:207], v235 offset:56320
	global_load_lds_dwordx4 v[208:209], off
	s_add_i32 m0, s18, 0x2000
	s_add_u32 s18, s22, 0xb0080
	v_lshl_add_u64 v[208:209], v[210:211], 0, s[12:13]
	s_addc_u32 s19, s23, 0
	s_add_i32 s22, s75, s30
	global_load_lds_dwordx4 v[208:209], off
	v_lshl_add_u64 v[208:209], s[18:19], 0, v[138:139]
	s_mov_b32 m0, s22
	s_nop 0
	global_load_lds_dwordx4 v[208:209], off
	v_lshl_add_u64 v[208:209], s[18:19], 0, v[142:143]
	s_add_i32 m0, s22, 0x2000
	s_nop 0
	global_load_lds_dwordx4 v[208:209], off
	v_lshl_add_u64 v[208:209], v[212:213], 0, s[12:13]
	s_mov_b32 m0, s55
	s_nop 0
	global_load_lds_dwordx4 v[208:209], off
	v_lshl_add_u64 v[208:209], v[214:215], 0, s[12:13]
	s_mov_b32 m0, s56
	s_nop 0
	global_load_lds_dwordx4 v[208:209], off
	s_waitcnt lgkmcnt(0)
	v_mfma_f32_16x16x32_bf16 v[92:95], v[96:99], v[176:179], v[92:95]
	s_waitcnt vmcnt(8)
	s_waitcnt lgkmcnt(0)
	s_barrier
	v_mfma_f32_16x16x32_bf16 v[88:91], v[152:155], v[176:179], v[88:91]
	v_mfma_f32_16x16x32_bf16 v[84:87], v[96:99], v[184:187], v[84:87]
	v_mfma_f32_16x16x32_bf16 v[80:83], v[152:155], v[184:187], v[80:83]
	v_mfma_f32_16x16x32_bf16 v[76:79], v[96:99], v[192:195], v[76:79]
	v_mfma_f32_16x16x32_bf16 v[72:75], v[152:155], v[192:195], v[72:75]
	v_mfma_f32_16x16x32_bf16 v[68:71], v[96:99], v[200:203], v[68:71]
	v_mfma_f32_16x16x32_bf16 v[64:67], v[152:155], v[200:203], v[64:67]
	v_mfma_f32_16x16x32_bf16 v[28:31], v[160:163], v[176:179], v[28:31]
	v_mfma_f32_16x16x32_bf16 v[24:27], v[168:171], v[176:179], v[24:27]
	v_mfma_f32_16x16x32_bf16 v[20:23], v[160:163], v[184:187], v[20:23]
	v_mfma_f32_16x16x32_bf16 v[16:19], v[168:171], v[184:187], v[16:19]
	v_mfma_f32_16x16x32_bf16 v[12:15], v[160:163], v[192:195], v[12:15]
	v_mfma_f32_16x16x32_bf16 v[8:11], v[168:171], v[192:195], v[8:11]
	v_mfma_f32_16x16x32_bf16 v[4:7], v[160:163], v[200:203], v[4:7]
	v_mfma_f32_16x16x32_bf16 v[0:3], v[168:171], v[200:203], v[0:3]
	v_mfma_f32_16x16x32_bf16 v[92:95], v[100:103], v[180:183], v[92:95]
	v_mfma_f32_16x16x32_bf16 v[88:91], v[156:159], v[180:183], v[88:91]
	v_mfma_f32_16x16x32_bf16 v[84:87], v[100:103], v[188:191], v[84:87]
	v_mfma_f32_16x16x32_bf16 v[80:83], v[156:159], v[188:191], v[80:83]
	v_mfma_f32_16x16x32_bf16 v[76:79], v[100:103], v[196:199], v[76:79]
	v_mfma_f32_16x16x32_bf16 v[72:75], v[156:159], v[196:199], v[72:75]
	v_mfma_f32_16x16x32_bf16 v[68:71], v[100:103], v[204:207], v[68:71]
	v_mfma_f32_16x16x32_bf16 v[64:67], v[156:159], v[204:207], v[64:67]
	v_mfma_f32_16x16x32_bf16 v[28:31], v[164:167], v[180:183], v[28:31]
	v_mfma_f32_16x16x32_bf16 v[24:27], v[172:175], v[180:183], v[24:27]
	v_mfma_f32_16x16x32_bf16 v[20:23], v[164:167], v[188:191], v[20:23]
	v_mfma_f32_16x16x32_bf16 v[16:19], v[172:175], v[188:191], v[16:19]
	v_mfma_f32_16x16x32_bf16 v[12:15], v[164:167], v[196:199], v[12:15]
	v_mfma_f32_16x16x32_bf16 v[8:11], v[172:175], v[196:199], v[8:11]
	v_mfma_f32_16x16x32_bf16 v[4:7], v[164:167], v[204:207], v[4:7]
	v_mfma_f32_16x16x32_bf16 v[0:3], v[172:175], v[204:207], v[0:3]
	s_barrier
	s_add_i32 s73, s73, 2
	s_add_u32 s67, s67, 0x100
	s_addc_u32 s72, s72, 0
	s_cmp_gt_u32 s73, 41
	s_mov_b64 s[18:19], s[20:21]
	s_cbranch_scc0 .LBB0_358
	s_and_b64 vcc, exec, s[14:15]
	s_cbranch_vccz .LBB0_361
	s_barrier

.LBB0_442:
	ds_read_b128 v[128:131], v181
	ds_read_b128 v[132:135], v181 offset:1024
	ds_read_b128 v[136:139], v181 offset:2048
	ds_read_b128 v[140:143], v181 offset:3072
	ds_read_b128 v[160:163], v182
	ds_read_b128 v[164:167], v182 offset:1024
	ds_read_b128 v[168:171], v182 offset:2048
	ds_read_b128 v[172:175], v182 offset:3072
	s_add_u32 s30, s28, 0xfffc0080
	s_addc_u32 s31, s29, -1
	s_cmp_eq_u32 s72, 12
	s_cselect_b32 s35, s21, s31
	s_cselect_b32 s34, s64, s30
	s_cselect_b32 s31, s19, s67
	s_cselect_b32 s30, s65, s66
	v_lshl_add_u64 v[176:177], s[28:29], 0, v[154:155]
	s_add_i32 m0, s42, 0xc000
	ds_read_b128 v[186:189], v183
	ds_read_b128 v[190:193], v183 offset:1024
	ds_read_b128 v[194:197], v183 offset:2048
	ds_read_b128 v[198:201], v183 offset:3072
	ds_read_b128 v[202:205], v183 offset:4096
	ds_read_b128 v[206:209], v183 offset:5120
	ds_read_b128 v[210:213], v183 offset:6144
	ds_read_b128 v[214:217], v183 offset:7168
	global_load_lds_dwordx4 v[176:177], off
	v_lshl_add_u64 v[176:177], s[28:29], 0, v[152:153]
	s_add_i32 m0, s42, 0xe000
	s_nop 0
	global_load_lds_dwordx4 v[176:177], off
	s_waitcnt lgkmcnt(0)
	v_mfma_f32_16x16x32_bf16 v[124:127], v[128:131], v[186:189], v[124:127]
	s_waitcnt vmcnt(8)
	s_waitcnt lgkmcnt(0)
	s_barrier
	v_mfma_f32_16x16x32_bf16 v[120:123], v[136:139], v[186:189], v[120:123]
	v_mfma_f32_16x16x32_bf16 v[108:111], v[128:131], v[194:197], v[108:111]
	v_mfma_f32_16x16x32_bf16 v[104:107], v[136:139], v[194:197], v[104:107]
	v_mfma_f32_16x16x32_bf16 v[92:95], v[128:131], v[202:205], v[92:95]
	v_mfma_f32_16x16x32_bf16 v[88:91], v[136:139], v[202:205], v[88:91]
	v_mfma_f32_16x16x32_bf16 v[76:79], v[128:131], v[210:213], v[76:79]
	v_mfma_f32_16x16x32_bf16 v[72:75], v[136:139], v[210:213], v[72:75]
	v_mfma_f32_16x16x32_bf16 v[116:119], v[160:163], v[186:189], v[116:119]
	v_mfma_f32_16x16x32_bf16 v[112:115], v[168:171], v[186:189], v[112:115]
	v_mfma_f32_16x16x32_bf16 v[100:103], v[160:163], v[194:197], v[100:103]
	v_mfma_f32_16x16x32_bf16 v[96:99], v[168:171], v[194:197], v[96:99]
	v_mfma_f32_16x16x32_bf16 v[84:87], v[160:163], v[202:205], v[84:87]
	v_mfma_f32_16x16x32_bf16 v[80:83], v[168:171], v[202:205], v[80:83]
	v_mfma_f32_16x16x32_bf16 v[68:71], v[160:163], v[210:213], v[68:71]
	v_mfma_f32_16x16x32_bf16 v[64:67], v[168:171], v[210:213], v[64:67]
	v_mfma_f32_16x16x32_bf16 v[124:127], v[132:135], v[190:193], v[124:127]
	v_mfma_f32_16x16x32_bf16 v[120:123], v[140:143], v[190:193], v[120:123]
	v_mfma_f32_16x16x32_bf16 v[108:111], v[132:135], v[198:201], v[108:111]
	v_mfma_f32_16x16x32_bf16 v[104:107], v[140:143], v[198:201], v[104:107]
	v_mfma_f32_16x16x32_bf16 v[92:95], v[132:135], v[206:209], v[92:95]
	v_mfma_f32_16x16x32_bf16 v[88:91], v[140:143], v[206:209], v[88:91]
	v_mfma_f32_16x16x32_bf16 v[76:79], v[132:135], v[214:217], v[76:79]
	v_mfma_f32_16x16x32_bf16 v[72:75], v[140:143], v[214:217], v[72:75]
	v_mfma_f32_16x16x32_bf16 v[116:119], v[164:167], v[190:193], v[116:119]
	v_mfma_f32_16x16x32_bf16 v[112:115], v[172:175], v[190:193], v[112:115]
	v_mfma_f32_16x16x32_bf16 v[100:103], v[164:167], v[198:201], v[100:103]
	v_mfma_f32_16x16x32_bf16 v[96:99], v[172:175], v[198:201], v[96:99]
	v_mfma_f32_16x16x32_bf16 v[84:87], v[164:167], v[206:209], v[84:87]
	v_mfma_f32_16x16x32_bf16 v[80:83], v[172:175], v[206:209], v[80:83]
	v_mfma_f32_16x16x32_bf16 v[68:71], v[164:167], v[214:217], v[68:71]
	v_mfma_f32_16x16x32_bf16 v[64:67], v[172:175], v[214:217], v[64:67]
	s_barrier
	s_add_i32 s73, s61, s41
	v_lshl_add_u64 v[176:177], s[30:31], 0, v[146:147]
	s_mov_b32 m0, s73
	ds_read_b128 v[186:189], v183 offset:16384
	ds_read_b128 v[190:193], v183 offset:17408
	ds_read_b128 v[194:197], v183 offset:18432
	ds_read_b128 v[198:201], v183 offset:19456
	ds_read_b128 v[202:205], v183 offset:20480
	ds_read_b128 v[206:209], v183 offset:21504
	ds_read_b128 v[210:213], v183 offset:22528
	ds_read_b128 v[214:217], v183 offset:23552
	global_load_lds_dwordx4 v[176:177], off
	s_add_i32 m0, s73, 0x2000
	s_add_u32 s74, s30, 0x40000
	v_lshl_add_u64 v[218:219], s[30:31], 0, v[150:151]
	s_addc_u32 s75, s31, 0
	s_add_i32 s73, s62, s41
	global_load_lds_dwordx4 v[218:219], off
	v_lshl_add_u64 v[220:221], s[74:75], 0, v[146:147]
	s_mov_b32 m0, s73
	v_lshl_add_u64 v[222:223], s[34:35], 0, v[148:149]
	global_load_lds_dwordx4 v[220:221], off
	v_lshl_add_u64 v[220:221], s[74:75], 0, v[150:151]
	s_add_i32 m0, s73, 0x2000
	s_nop 0
	global_load_lds_dwordx4 v[220:221], off
	v_lshl_add_u64 v[220:221], s[34:35], 0, v[144:145]
	s_mov_b32 m0, s42
	s_nop 0
	global_load_lds_dwordx4 v[220:221], off
	s_mov_b32 m0, s43
	s_nop 0
	global_load_lds_dwordx4 v[222:223], off
	s_waitcnt lgkmcnt(0)
	v_mfma_f32_16x16x32_bf16 v[60:63], v[128:131], v[186:189], v[60:63]
	s_waitcnt vmcnt(8)
	s_waitcnt lgkmcnt(0)
	s_barrier
	v_mfma_f32_16x16x32_bf16 v[56:59], v[136:139], v[186:189], v[56:59]
	v_mfma_f32_16x16x32_bf16 v[44:47], v[128:131], v[194:197], v[44:47]
	v_mfma_f32_16x16x32_bf16 v[40:43], v[136:139], v[194:197], v[40:43]
	v_mfma_f32_16x16x32_bf16 v[28:31], v[128:131], v[202:205], v[28:31]
	v_mfma_f32_16x16x32_bf16 v[24:27], v[136:139], v[202:205], v[24:27]
	v_mfma_f32_16x16x32_bf16 v[12:15], v[128:131], v[210:213], v[12:15]
	v_mfma_f32_16x16x32_bf16 v[8:11], v[136:139], v[210:213], v[8:11]
	v_mfma_f32_16x16x32_bf16 v[52:55], v[160:163], v[186:189], v[52:55]
	v_mfma_f32_16x16x32_bf16 v[48:51], v[168:171], v[186:189], v[48:51]
	v_mfma_f32_16x16x32_bf16 v[36:39], v[160:163], v[194:197], v[36:39]
	v_mfma_f32_16x16x32_bf16 v[32:35], v[168:171], v[194:197], v[32:35]
	v_mfma_f32_16x16x32_bf16 v[20:23], v[160:163], v[202:205], v[20:23]
	v_mfma_f32_16x16x32_bf16 v[16:19], v[168:171], v[202:205], v[16:19]
	v_mfma_f32_16x16x32_bf16 v[4:7], v[160:163], v[210:213], v[4:7]
	v_mfma_f32_16x16x32_bf16 v[0:3], v[168:171], v[210:213], v[0:3]
	v_mfma_f32_16x16x32_bf16 v[60:63], v[132:135], v[190:193], v[60:63]
	v_mfma_f32_16x16x32_bf16 v[56:59], v[140:143], v[190:193], v[56:59]
	v_mfma_f32_16x16x32_bf16 v[44:47], v[132:135], v[198:201], v[44:47]
	v_mfma_f32_16x16x32_bf16 v[40:43], v[140:143], v[198:201], v[40:43]
	v_mfma_f32_16x16x32_bf16 v[28:31], v[132:135], v[206:209], v[28:31]
	v_mfma_f32_16x16x32_bf16 v[24:27], v[140:143], v[206:209], v[24:27]
	v_mfma_f32_16x16x32_bf16 v[12:15], v[132:135], v[214:217], v[12:15]
	v_mfma_f32_16x16x32_bf16 v[8:11], v[140:143], v[214:217], v[8:11]
	v_mfma_f32_16x16x32_bf16 v[52:55], v[164:167], v[190:193], v[52:55]
	v_mfma_f32_16x16x32_bf16 v[48:51], v[172:175], v[190:193], v[48:51]
	v_mfma_f32_16x16x32_bf16 v[36:39], v[164:167], v[198:201], v[36:39]
	v_mfma_f32_16x16x32_bf16 v[32:35], v[172:175], v[198:201], v[32:35]
	v_mfma_f32_16x16x32_bf16 v[20:23], v[164:167], v[206:209], v[20:23]
	v_mfma_f32_16x16x32_bf16 v[16:19], v[172:175], v[206:209], v[16:19]
	v_mfma_f32_16x16x32_bf16 v[4:7], v[164:167], v[214:217], v[4:7]
	v_mfma_f32_16x16x32_bf16 v[0:3], v[172:175], v[214:217], v[0:3]
	s_barrier
	s_add_i32 s73, 0, 0x18000
	s_add_i32 s74, 0, 0x1c000
	v_add_u32_e32 v140, s73, v180
	v_add_u32_e32 v172, s74, v180
	ds_read_b128 v[128:131], v140
	ds_read_b128 v[132:135], v140 offset:1024
	ds_read_b128 v[136:139], v140 offset:2048
	ds_read_b128 v[140:143], v140 offset:3072
	ds_read_b128 v[160:163], v172
	ds_read_b128 v[164:167], v172 offset:1024
	ds_read_b128 v[168:171], v172 offset:2048
	ds_read_b128 v[172:175], v172 offset:3072
	s_add_u32 s34, s34, 0x40000
	s_addc_u32 s35, s35, 0
	s_mov_b32 m0, s44
	v_lshl_add_u64 v[224:225], s[34:35], 0, v[144:145]
	ds_read_b128 v[186:189], v183 offset:32768
	ds_read_b128 v[190:193], v183 offset:33792
	ds_read_b128 v[194:197], v183 offset:34816
	ds_read_b128 v[198:201], v183 offset:35840
	ds_read_b128 v[202:205], v183 offset:36864
	ds_read_b128 v[206:209], v183 offset:37888
	ds_read_b128 v[210:213], v183 offset:38912
	ds_read_b128 v[214:217], v183 offset:39936
	global_load_lds_dwordx4 v[224:225], off
	v_lshl_add_u64 v[224:225], s[34:35], 0, v[148:149]
	s_mov_b32 m0, s45
	s_nop 0
	global_load_lds_dwordx4 v[224:225], off
	s_waitcnt lgkmcnt(0)
	v_mfma_f32_16x16x32_bf16 v[124:127], v[128:131], v[186:189], v[124:127]
	s_waitcnt vmcnt(8)
	s_waitcnt lgkmcnt(0)
	s_barrier
	v_mfma_f32_16x16x32_bf16 v[120:123], v[136:139], v[186:189], v[120:123]
	v_mfma_f32_16x16x32_bf16 v[108:111], v[128:131], v[194:197], v[108:111]
	v_mfma_f32_16x16x32_bf16 v[104:107], v[136:139], v[194:197], v[104:107]
	v_mfma_f32_16x16x32_bf16 v[92:95], v[128:131], v[202:205], v[92:95]
	v_mfma_f32_16x16x32_bf16 v[88:91], v[136:139], v[202:205], v[88:91]
	v_mfma_f32_16x16x32_bf16 v[76:79], v[128:131], v[210:213], v[76:79]
	v_mfma_f32_16x16x32_bf16 v[72:75], v[136:139], v[210:213], v[72:75]
	v_mfma_f32_16x16x32_bf16 v[116:119], v[160:163], v[186:189], v[116:119]
	v_mfma_f32_16x16x32_bf16 v[112:115], v[168:171], v[186:189], v[112:115]
	v_mfma_f32_16x16x32_bf16 v[100:103], v[160:163], v[194:197], v[100:103]
	v_mfma_f32_16x16x32_bf16 v[96:99], v[168:171], v[194:197], v[96:99]
	v_mfma_f32_16x16x32_bf16 v[84:87], v[160:163], v[202:205], v[84:87]
	v_mfma_f32_16x16x32_bf16 v[80:83], v[168:171], v[202:205], v[80:83]
	v_mfma_f32_16x16x32_bf16 v[68:71], v[160:163], v[210:213], v[68:71]
	v_mfma_f32_16x16x32_bf16 v[64:67], v[168:171], v[210:213], v[64:67]
	v_mfma_f32_16x16x32_bf16 v[124:127], v[132:135], v[190:193], v[124:127]
	v_mfma_f32_16x16x32_bf16 v[120:123], v[140:143], v[190:193], v[120:123]
	v_mfma_f32_16x16x32_bf16 v[108:111], v[132:135], v[198:201], v[108:111]
	v_mfma_f32_16x16x32_bf16 v[104:107], v[140:143], v[198:201], v[104:107]
	v_mfma_f32_16x16x32_bf16 v[92:95], v[132:135], v[206:209], v[92:95]
	v_mfma_f32_16x16x32_bf16 v[88:91], v[140:143], v[206:209], v[88:91]
	v_mfma_f32_16x16x32_bf16 v[76:79], v[132:135], v[214:217], v[76:79]
	v_mfma_f32_16x16x32_bf16 v[72:75], v[140:143], v[214:217], v[72:75]
	v_mfma_f32_16x16x32_bf16 v[116:119], v[164:167], v[190:193], v[116:119]
	v_mfma_f32_16x16x32_bf16 v[112:115], v[172:175], v[190:193], v[112:115]
	v_mfma_f32_16x16x32_bf16 v[100:103], v[164:167], v[198:201], v[100:103]
	v_mfma_f32_16x16x32_bf16 v[96:99], v[172:175], v[198:201], v[96:99]
	v_mfma_f32_16x16x32_bf16 v[84:87], v[164:167], v[206:209], v[84:87]
	v_mfma_f32_16x16x32_bf16 v[80:83], v[172:175], v[206:209], v[80:83]
	v_mfma_f32_16x16x32_bf16 v[68:71], v[164:167], v[214:217], v[68:71]
	v_mfma_f32_16x16x32_bf16 v[64:67], v[172:175], v[214:217], v[64:67]
	s_barrier
	s_add_i32 s34, s73, s41
	v_lshl_add_u64 v[176:177], v[176:177], 0, s[10:11]
	s_mov_b32 m0, s34
	ds_read_b128 v[186:189], v183 offset:49152
	ds_read_b128 v[190:193], v183 offset:50176
	ds_read_b128 v[194:197], v183 offset:51200
	ds_read_b128 v[198:201], v183 offset:52224
	ds_read_b128 v[202:205], v183 offset:53248
	ds_read_b128 v[206:209], v183 offset:54272
	ds_read_b128 v[210:213], v183 offset:55296
	ds_read_b128 v[214:217], v183 offset:56320
	global_load_lds_dwordx4 v[176:177], off
	s_add_i32 m0, s34, 0x2000
	s_add_u32 s30, s30, 0x40080
	v_lshl_add_u64 v[176:177], v[218:219], 0, s[10:11]
	s_addc_u32 s31, s31, 0
	s_add_i32 s34, s74, s41
	global_load_lds_dwordx4 v[176:177], off
	v_lshl_add_u64 v[176:177], s[30:31], 0, v[146:147]
	s_mov_b32 m0, s34
	s_nop 0
	global_load_lds_dwordx4 v[176:177], off
	v_lshl_add_u64 v[176:177], s[30:31], 0, v[150:151]
	s_add_i32 m0, s34, 0x2000
	s_nop 0
	global_load_lds_dwordx4 v[176:177], off
	v_lshl_add_u64 v[176:177], v[220:221], 0, s[10:11]
	s_mov_b32 m0, s58
	s_nop 0
	global_load_lds_dwordx4 v[176:177], off
	v_lshl_add_u64 v[176:177], v[222:223], 0, s[10:11]
	s_mov_b32 m0, s59
	s_nop 0
	global_load_lds_dwordx4 v[176:177], off
	s_waitcnt lgkmcnt(0)
	v_mfma_f32_16x16x32_bf16 v[60:63], v[128:131], v[186:189], v[60:63]
	s_waitcnt vmcnt(8)
	s_waitcnt lgkmcnt(0)
	s_barrier
	v_mfma_f32_16x16x32_bf16 v[56:59], v[136:139], v[186:189], v[56:59]
	v_mfma_f32_16x16x32_bf16 v[44:47], v[128:131], v[194:197], v[44:47]
	v_mfma_f32_16x16x32_bf16 v[40:43], v[136:139], v[194:197], v[40:43]
	v_mfma_f32_16x16x32_bf16 v[28:31], v[128:131], v[202:205], v[28:31]
	v_mfma_f32_16x16x32_bf16 v[24:27], v[136:139], v[202:205], v[24:27]
	v_mfma_f32_16x16x32_bf16 v[12:15], v[128:131], v[210:213], v[12:15]
	v_mfma_f32_16x16x32_bf16 v[8:11], v[136:139], v[210:213], v[8:11]
	v_mfma_f32_16x16x32_bf16 v[52:55], v[160:163], v[186:189], v[52:55]
	v_mfma_f32_16x16x32_bf16 v[48:51], v[168:171], v[186:189], v[48:51]
	v_mfma_f32_16x16x32_bf16 v[36:39], v[160:163], v[194:197], v[36:39]
	v_mfma_f32_16x16x32_bf16 v[32:35], v[168:171], v[194:197], v[32:35]
	v_mfma_f32_16x16x32_bf16 v[20:23], v[160:163], v[202:205], v[20:23]
	v_mfma_f32_16x16x32_bf16 v[16:19], v[168:171], v[202:205], v[16:19]
	v_mfma_f32_16x16x32_bf16 v[4:7], v[160:163], v[210:213], v[4:7]
	v_mfma_f32_16x16x32_bf16 v[0:3], v[168:171], v[210:213], v[0:3]
	v_mfma_f32_16x16x32_bf16 v[60:63], v[132:135], v[190:193], v[60:63]
	v_mfma_f32_16x16x32_bf16 v[56:59], v[140:143], v[190:193], v[56:59]
	v_mfma_f32_16x16x32_bf16 v[44:47], v[132:135], v[198:201], v[44:47]
	v_mfma_f32_16x16x32_bf16 v[40:43], v[140:143], v[198:201], v[40:43]
	v_mfma_f32_16x16x32_bf16 v[28:31], v[132:135], v[206:209], v[28:31]
	v_mfma_f32_16x16x32_bf16 v[24:27], v[140:143], v[206:209], v[24:27]
	v_mfma_f32_16x16x32_bf16 v[12:15], v[132:135], v[214:217], v[12:15]
	v_mfma_f32_16x16x32_bf16 v[8:11], v[140:143], v[214:217], v[8:11]
	v_mfma_f32_16x16x32_bf16 v[52:55], v[164:167], v[190:193], v[52:55]
	v_mfma_f32_16x16x32_bf16 v[48:51], v[172:175], v[190:193], v[48:51]
	v_mfma_f32_16x16x32_bf16 v[36:39], v[164:167], v[198:201], v[36:39]
	v_mfma_f32_16x16x32_bf16 v[32:35], v[172:175], v[198:201], v[32:35]
	v_mfma_f32_16x16x32_bf16 v[20:23], v[164:167], v[206:209], v[20:23]
	v_mfma_f32_16x16x32_bf16 v[16:19], v[172:175], v[206:209], v[16:19]
	v_mfma_f32_16x16x32_bf16 v[4:7], v[164:167], v[214:217], v[4:7]
	v_mfma_f32_16x16x32_bf16 v[0:3], v[172:175], v[214:217], v[0:3]
	s_barrier
	s_add_i32 s72, s72, 2
	s_add_u32 s66, s66, 0x100
	s_addc_u32 s67, s67, 0
	s_add_u32 s28, s28, 0x100
	s_addc_u32 s29, s29, 0
	s_cmp_gt_u32 s72, 13
	s_cbranch_scc0 .LBB0_442
	s_and_b64 vcc, exec, s[12:13]
	s_cbranch_vccz .LBB0_445
	s_barrier

.LBB0_760:
	ds_read_b128 v[144:147], v151
	ds_read_b128 v[154:157], v151 offset:1024
	ds_read_b128 v[158:161], v151 offset:2048
	ds_read_b128 v[162:165], v151 offset:3072
	ds_read_b128 v[166:169], v152
	ds_read_b128 v[170:173], v152 offset:1024
	ds_read_b128 v[174:177], v152 offset:2048
	ds_read_b128 v[178:181], v152 offset:3072
	s_add_u32 s26, s24, 0xfffe0080
	s_addc_u32 s27, s25, -1
	s_cmp_eq_u32 s56, 4
	s_cselect_b32 s29, s17, s27
	s_cselect_b32 s28, s52, s26
	s_cselect_b32 s27, s15, s55
	s_cselect_b32 s26, s53, s54
	v_lshl_add_u64 v[214:215], s[24:25], 0, v[138:139]
	s_add_i32 m0, s23, 0xc000
	ds_read_b128 v[182:185], v153
	ds_read_b128 v[186:189], v153 offset:1024
	ds_read_b128 v[190:193], v153 offset:2048
	ds_read_b128 v[194:197], v153 offset:3072
	ds_read_b128 v[198:201], v153 offset:4096
	ds_read_b128 v[202:205], v153 offset:5120
	ds_read_b128 v[206:209], v153 offset:6144
	ds_read_b128 v[210:213], v153 offset:7168
	global_load_lds_dwordx4 v[214:215], off
	v_lshl_add_u64 v[214:215], s[24:25], 0, v[136:137]
	s_add_i32 m0, s23, 0xe000
	s_nop 0
	global_load_lds_dwordx4 v[214:215], off
	s_waitcnt lgkmcnt(0)
	v_mfma_f32_16x16x32_bf16 v[124:127], v[144:147], v[182:185], v[124:127]
	s_waitcnt vmcnt(8)
	s_waitcnt lgkmcnt(0)
	s_barrier
	v_mfma_f32_16x16x32_bf16 v[120:123], v[158:161], v[182:185], v[120:123]
	v_mfma_f32_16x16x32_bf16 v[108:111], v[144:147], v[190:193], v[108:111]
	v_mfma_f32_16x16x32_bf16 v[104:107], v[158:161], v[190:193], v[104:107]
	v_mfma_f32_16x16x32_bf16 v[92:95], v[144:147], v[198:201], v[92:95]
	v_mfma_f32_16x16x32_bf16 v[88:91], v[158:161], v[198:201], v[88:91]
	v_mfma_f32_16x16x32_bf16 v[76:79], v[144:147], v[206:209], v[76:79]
	v_mfma_f32_16x16x32_bf16 v[72:75], v[158:161], v[206:209], v[72:75]
	v_mfma_f32_16x16x32_bf16 v[116:119], v[166:169], v[182:185], v[116:119]
	v_mfma_f32_16x16x32_bf16 v[112:115], v[174:177], v[182:185], v[112:115]
	v_mfma_f32_16x16x32_bf16 v[100:103], v[166:169], v[190:193], v[100:103]
	v_mfma_f32_16x16x32_bf16 v[96:99], v[174:177], v[190:193], v[96:99]
	v_mfma_f32_16x16x32_bf16 v[84:87], v[166:169], v[198:201], v[84:87]
	v_mfma_f32_16x16x32_bf16 v[80:83], v[174:177], v[198:201], v[80:83]
	v_mfma_f32_16x16x32_bf16 v[68:71], v[166:169], v[206:209], v[68:71]
	v_mfma_f32_16x16x32_bf16 v[64:67], v[174:177], v[206:209], v[64:67]
	v_mfma_f32_16x16x32_bf16 v[124:127], v[154:157], v[186:189], v[124:127]
	v_mfma_f32_16x16x32_bf16 v[120:123], v[162:165], v[186:189], v[120:123]
	v_mfma_f32_16x16x32_bf16 v[108:111], v[154:157], v[194:197], v[108:111]
	v_mfma_f32_16x16x32_bf16 v[104:107], v[162:165], v[194:197], v[104:107]
	v_mfma_f32_16x16x32_bf16 v[92:95], v[154:157], v[202:205], v[92:95]
	v_mfma_f32_16x16x32_bf16 v[88:91], v[162:165], v[202:205], v[88:91]
	v_mfma_f32_16x16x32_bf16 v[76:79], v[154:157], v[210:213], v[76:79]
	v_mfma_f32_16x16x32_bf16 v[72:75], v[162:165], v[210:213], v[72:75]
	v_mfma_f32_16x16x32_bf16 v[116:119], v[170:173], v[186:189], v[116:119]
	v_mfma_f32_16x16x32_bf16 v[112:115], v[178:181], v[186:189], v[112:115]
	v_mfma_f32_16x16x32_bf16 v[100:103], v[170:173], v[194:197], v[100:103]
	v_mfma_f32_16x16x32_bf16 v[96:99], v[178:181], v[194:197], v[96:99]
	v_mfma_f32_16x16x32_bf16 v[84:87], v[170:173], v[202:205], v[84:87]
	v_mfma_f32_16x16x32_bf16 v[80:83], v[178:181], v[202:205], v[80:83]
	v_mfma_f32_16x16x32_bf16 v[68:71], v[170:173], v[210:213], v[68:71]
	v_mfma_f32_16x16x32_bf16 v[64:67], v[178:181], v[210:213], v[64:67]
	s_barrier
	s_add_i32 s57, s49, s39
	v_lshl_add_u64 v[214:215], s[26:27], 0, v[130:131]
	s_mov_b32 m0, s57
	ds_read_b128 v[182:185], v153 offset:16384
	ds_read_b128 v[186:189], v153 offset:17408
	ds_read_b128 v[190:193], v153 offset:18432
	ds_read_b128 v[194:197], v153 offset:19456
	ds_read_b128 v[198:201], v153 offset:20480
	ds_read_b128 v[202:205], v153 offset:21504
	ds_read_b128 v[206:209], v153 offset:22528
	ds_read_b128 v[210:213], v153 offset:23552
	global_load_lds_dwordx4 v[214:215], off
	s_add_i32 m0, s57, 0x2000
	s_add_u32 s58, s26, 0x20000
	v_lshl_add_u64 v[216:217], s[26:27], 0, v[134:135]
	s_addc_u32 s59, s27, 0
	s_add_i32 s57, s50, s39
	global_load_lds_dwordx4 v[216:217], off
	v_lshl_add_u64 v[218:219], s[58:59], 0, v[130:131]
	s_mov_b32 m0, s57
	v_lshl_add_u64 v[220:221], s[28:29], 0, v[132:133]
	global_load_lds_dwordx4 v[218:219], off
	v_lshl_add_u64 v[218:219], s[58:59], 0, v[134:135]
	s_add_i32 m0, s57, 0x2000
	s_nop 0
	global_load_lds_dwordx4 v[218:219], off
	v_lshl_add_u64 v[218:219], s[28:29], 0, v[128:129]
	s_mov_b32 m0, s23
	s_nop 0
	global_load_lds_dwordx4 v[218:219], off
	s_mov_b32 m0, s40
	s_nop 0
	global_load_lds_dwordx4 v[220:221], off
	s_waitcnt lgkmcnt(0)
	v_mfma_f32_16x16x32_bf16 v[60:63], v[144:147], v[182:185], v[60:63]
	s_waitcnt vmcnt(8)
	s_waitcnt lgkmcnt(0)
	s_barrier
	v_mfma_f32_16x16x32_bf16 v[56:59], v[158:161], v[182:185], v[56:59]
	v_mfma_f32_16x16x32_bf16 v[44:47], v[144:147], v[190:193], v[44:47]
	v_mfma_f32_16x16x32_bf16 v[40:43], v[158:161], v[190:193], v[40:43]
	v_mfma_f32_16x16x32_bf16 v[28:31], v[144:147], v[198:201], v[28:31]
	v_mfma_f32_16x16x32_bf16 v[24:27], v[158:161], v[198:201], v[24:27]
	v_mfma_f32_16x16x32_bf16 v[12:15], v[144:147], v[206:209], v[12:15]
	v_mfma_f32_16x16x32_bf16 v[8:11], v[158:161], v[206:209], v[8:11]
	v_mfma_f32_16x16x32_bf16 v[52:55], v[166:169], v[182:185], v[52:55]
	v_mfma_f32_16x16x32_bf16 v[48:51], v[174:177], v[182:185], v[48:51]
	v_mfma_f32_16x16x32_bf16 v[36:39], v[166:169], v[190:193], v[36:39]
	v_mfma_f32_16x16x32_bf16 v[32:35], v[174:177], v[190:193], v[32:35]
	v_mfma_f32_16x16x32_bf16 v[20:23], v[166:169], v[198:201], v[20:23]
	v_mfma_f32_16x16x32_bf16 v[16:19], v[174:177], v[198:201], v[16:19]
	v_mfma_f32_16x16x32_bf16 v[4:7], v[166:169], v[206:209], v[4:7]
	v_mfma_f32_16x16x32_bf16 v[0:3], v[174:177], v[206:209], v[0:3]
	v_mfma_f32_16x16x32_bf16 v[60:63], v[154:157], v[186:189], v[60:63]
	v_mfma_f32_16x16x32_bf16 v[56:59], v[162:165], v[186:189], v[56:59]
	v_mfma_f32_16x16x32_bf16 v[44:47], v[154:157], v[194:197], v[44:47]
	v_mfma_f32_16x16x32_bf16 v[40:43], v[162:165], v[194:197], v[40:43]
	v_mfma_f32_16x16x32_bf16 v[28:31], v[154:157], v[202:205], v[28:31]
	v_mfma_f32_16x16x32_bf16 v[24:27], v[162:165], v[202:205], v[24:27]
	v_mfma_f32_16x16x32_bf16 v[12:15], v[154:157], v[210:213], v[12:15]
	v_mfma_f32_16x16x32_bf16 v[8:11], v[162:165], v[210:213], v[8:11]
	v_mfma_f32_16x16x32_bf16 v[52:55], v[170:173], v[186:189], v[52:55]
	v_mfma_f32_16x16x32_bf16 v[48:51], v[178:181], v[186:189], v[48:51]
	v_mfma_f32_16x16x32_bf16 v[36:39], v[170:173], v[194:197], v[36:39]
	v_mfma_f32_16x16x32_bf16 v[32:35], v[178:181], v[194:197], v[32:35]
	v_mfma_f32_16x16x32_bf16 v[20:23], v[170:173], v[202:205], v[20:23]
	v_mfma_f32_16x16x32_bf16 v[16:19], v[178:181], v[202:205], v[16:19]
	v_mfma_f32_16x16x32_bf16 v[4:7], v[170:173], v[210:213], v[4:7]
	v_mfma_f32_16x16x32_bf16 v[0:3], v[178:181], v[210:213], v[0:3]
	s_barrier
	s_add_i32 s57, 0, 0x18000
	s_add_i32 s58, 0, 0x1c000
	v_add_u32_e32 v162, s57, v150
	v_add_u32_e32 v178, s58, v150
	ds_read_b128 v[144:147], v162
	ds_read_b128 v[154:157], v162 offset:1024
	ds_read_b128 v[158:161], v162 offset:2048
	ds_read_b128 v[162:165], v162 offset:3072
	ds_read_b128 v[166:169], v178
	ds_read_b128 v[170:173], v178 offset:1024
	ds_read_b128 v[174:177], v178 offset:2048
	ds_read_b128 v[178:181], v178 offset:3072
	s_add_u32 s28, s28, 0x20000
	s_addc_u32 s29, s29, 0
	s_mov_b32 m0, s41
	v_lshl_add_u64 v[222:223], s[28:29], 0, v[128:129]
	ds_read_b128 v[182:185], v153 offset:32768
	ds_read_b128 v[186:189], v153 offset:33792
	ds_read_b128 v[190:193], v153 offset:34816
	ds_read_b128 v[194:197], v153 offset:35840
	ds_read_b128 v[198:201], v153 offset:36864
	ds_read_b128 v[202:205], v153 offset:37888
	ds_read_b128 v[206:209], v153 offset:38912
	ds_read_b128 v[210:213], v153 offset:39936
	global_load_lds_dwordx4 v[222:223], off
	v_lshl_add_u64 v[222:223], s[28:29], 0, v[132:133]
	s_mov_b32 m0, s42
	s_nop 0
	global_load_lds_dwordx4 v[222:223], off
	s_waitcnt lgkmcnt(0)
	v_mfma_f32_16x16x32_bf16 v[124:127], v[144:147], v[182:185], v[124:127]
	s_waitcnt vmcnt(8)
	s_waitcnt lgkmcnt(0)
	s_barrier
	v_mfma_f32_16x16x32_bf16 v[120:123], v[158:161], v[182:185], v[120:123]
	v_mfma_f32_16x16x32_bf16 v[108:111], v[144:147], v[190:193], v[108:111]
	v_mfma_f32_16x16x32_bf16 v[104:107], v[158:161], v[190:193], v[104:107]
	v_mfma_f32_16x16x32_bf16 v[92:95], v[144:147], v[198:201], v[92:95]
	v_mfma_f32_16x16x32_bf16 v[88:91], v[158:161], v[198:201], v[88:91]
	v_mfma_f32_16x16x32_bf16 v[76:79], v[144:147], v[206:209], v[76:79]
	v_mfma_f32_16x16x32_bf16 v[72:75], v[158:161], v[206:209], v[72:75]
	v_mfma_f32_16x16x32_bf16 v[116:119], v[166:169], v[182:185], v[116:119]
	v_mfma_f32_16x16x32_bf16 v[112:115], v[174:177], v[182:185], v[112:115]
	v_mfma_f32_16x16x32_bf16 v[100:103], v[166:169], v[190:193], v[100:103]
	v_mfma_f32_16x16x32_bf16 v[96:99], v[174:177], v[190:193], v[96:99]
	v_mfma_f32_16x16x32_bf16 v[84:87], v[166:169], v[198:201], v[84:87]
	v_mfma_f32_16x16x32_bf16 v[80:83], v[174:177], v[198:201], v[80:83]
	v_mfma_f32_16x16x32_bf16 v[68:71], v[166:169], v[206:209], v[68:71]
	v_mfma_f32_16x16x32_bf16 v[64:67], v[174:177], v[206:209], v[64:67]
	v_mfma_f32_16x16x32_bf16 v[124:127], v[154:157], v[186:189], v[124:127]
	v_mfma_f32_16x16x32_bf16 v[120:123], v[162:165], v[186:189], v[120:123]
	v_mfma_f32_16x16x32_bf16 v[108:111], v[154:157], v[194:197], v[108:111]
	v_mfma_f32_16x16x32_bf16 v[104:107], v[162:165], v[194:197], v[104:107]
	v_mfma_f32_16x16x32_bf16 v[92:95], v[154:157], v[202:205], v[92:95]
	v_mfma_f32_16x16x32_bf16 v[88:91], v[162:165], v[202:205], v[88:91]
	v_mfma_f32_16x16x32_bf16 v[76:79], v[154:157], v[210:213], v[76:79]
	v_mfma_f32_16x16x32_bf16 v[72:75], v[162:165], v[210:213], v[72:75]
	v_mfma_f32_16x16x32_bf16 v[116:119], v[170:173], v[186:189], v[116:119]
	v_mfma_f32_16x16x32_bf16 v[112:115], v[178:181], v[186:189], v[112:115]
	v_mfma_f32_16x16x32_bf16 v[100:103], v[170:173], v[194:197], v[100:103]
	v_mfma_f32_16x16x32_bf16 v[96:99], v[178:181], v[194:197], v[96:99]
	v_mfma_f32_16x16x32_bf16 v[84:87], v[170:173], v[202:205], v[84:87]
	v_mfma_f32_16x16x32_bf16 v[80:83], v[178:181], v[202:205], v[80:83]
	v_mfma_f32_16x16x32_bf16 v[68:71], v[170:173], v[210:213], v[68:71]
	v_mfma_f32_16x16x32_bf16 v[64:67], v[178:181], v[210:213], v[64:67]
	s_barrier
	s_add_i32 s28, s57, s39
	v_lshl_add_u64 v[214:215], v[214:215], 0, s[10:11]
	s_mov_b32 m0, s28
	ds_read_b128 v[182:185], v153 offset:49152
	ds_read_b128 v[186:189], v153 offset:50176
	ds_read_b128 v[190:193], v153 offset:51200
	ds_read_b128 v[194:197], v153 offset:52224
	ds_read_b128 v[198:201], v153 offset:53248
	ds_read_b128 v[202:205], v153 offset:54272
	ds_read_b128 v[206:209], v153 offset:55296
	ds_read_b128 v[210:213], v153 offset:56320
	global_load_lds_dwordx4 v[214:215], off
	s_add_i32 m0, s28, 0x2000
	s_add_u32 s26, s26, 0x20080
	v_lshl_add_u64 v[214:215], v[216:217], 0, s[10:11]
	s_addc_u32 s27, s27, 0
	s_add_i32 s28, s58, s39
	global_load_lds_dwordx4 v[214:215], off
	v_lshl_add_u64 v[214:215], s[26:27], 0, v[130:131]
	s_mov_b32 m0, s28
	s_nop 0
	global_load_lds_dwordx4 v[214:215], off
	v_lshl_add_u64 v[214:215], s[26:27], 0, v[134:135]
	s_add_i32 m0, s28, 0x2000
	s_nop 0
	global_load_lds_dwordx4 v[214:215], off
	v_lshl_add_u64 v[214:215], v[218:219], 0, s[10:11]
	s_mov_b32 m0, s46
	s_nop 0
	global_load_lds_dwordx4 v[214:215], off
	v_lshl_add_u64 v[214:215], v[220:221], 0, s[10:11]
	s_mov_b32 m0, s47
	s_nop 0
	global_load_lds_dwordx4 v[214:215], off
	s_waitcnt lgkmcnt(0)
	v_mfma_f32_16x16x32_bf16 v[60:63], v[144:147], v[182:185], v[60:63]
	s_waitcnt vmcnt(8)
	s_waitcnt lgkmcnt(0)
	s_barrier
	v_mfma_f32_16x16x32_bf16 v[56:59], v[158:161], v[182:185], v[56:59]
	v_mfma_f32_16x16x32_bf16 v[44:47], v[144:147], v[190:193], v[44:47]
	v_mfma_f32_16x16x32_bf16 v[40:43], v[158:161], v[190:193], v[40:43]
	v_mfma_f32_16x16x32_bf16 v[28:31], v[144:147], v[198:201], v[28:31]
	v_mfma_f32_16x16x32_bf16 v[24:27], v[158:161], v[198:201], v[24:27]
	v_mfma_f32_16x16x32_bf16 v[12:15], v[144:147], v[206:209], v[12:15]
	v_mfma_f32_16x16x32_bf16 v[8:11], v[158:161], v[206:209], v[8:11]
	v_mfma_f32_16x16x32_bf16 v[52:55], v[166:169], v[182:185], v[52:55]
	v_mfma_f32_16x16x32_bf16 v[48:51], v[174:177], v[182:185], v[48:51]
	v_mfma_f32_16x16x32_bf16 v[36:39], v[166:169], v[190:193], v[36:39]
	v_mfma_f32_16x16x32_bf16 v[32:35], v[174:177], v[190:193], v[32:35]
	v_mfma_f32_16x16x32_bf16 v[20:23], v[166:169], v[198:201], v[20:23]
	v_mfma_f32_16x16x32_bf16 v[16:19], v[174:177], v[198:201], v[16:19]
	v_mfma_f32_16x16x32_bf16 v[4:7], v[166:169], v[206:209], v[4:7]
	v_mfma_f32_16x16x32_bf16 v[0:3], v[174:177], v[206:209], v[0:3]
	v_mfma_f32_16x16x32_bf16 v[60:63], v[154:157], v[186:189], v[60:63]
	v_mfma_f32_16x16x32_bf16 v[56:59], v[162:165], v[186:189], v[56:59]
	v_mfma_f32_16x16x32_bf16 v[44:47], v[154:157], v[194:197], v[44:47]
	v_mfma_f32_16x16x32_bf16 v[40:43], v[162:165], v[194:197], v[40:43]
	v_mfma_f32_16x16x32_bf16 v[28:31], v[154:157], v[202:205], v[28:31]
	v_mfma_f32_16x16x32_bf16 v[24:27], v[162:165], v[202:205], v[24:27]
	v_mfma_f32_16x16x32_bf16 v[12:15], v[154:157], v[210:213], v[12:15]
	v_mfma_f32_16x16x32_bf16 v[8:11], v[162:165], v[210:213], v[8:11]
	v_mfma_f32_16x16x32_bf16 v[52:55], v[170:173], v[186:189], v[52:55]
	v_mfma_f32_16x16x32_bf16 v[48:51], v[178:181], v[186:189], v[48:51]
	v_mfma_f32_16x16x32_bf16 v[36:39], v[170:173], v[194:197], v[36:39]
	v_mfma_f32_16x16x32_bf16 v[32:35], v[178:181], v[194:197], v[32:35]
	v_mfma_f32_16x16x32_bf16 v[20:23], v[170:173], v[202:205], v[20:23]
	v_mfma_f32_16x16x32_bf16 v[16:19], v[178:181], v[202:205], v[16:19]
	v_mfma_f32_16x16x32_bf16 v[4:7], v[170:173], v[210:213], v[4:7]
	v_mfma_f32_16x16x32_bf16 v[0:3], v[178:181], v[210:213], v[0:3]
	s_barrier
	s_add_i32 s56, s56, 2
	s_add_u32 s54, s54, 0x100
	s_addc_u32 s55, s55, 0
	s_add_u32 s24, s24, 0x100
	s_addc_u32 s25, s25, 0
	s_cmp_gt_u32 s56, 5
	s_cbranch_scc0 .LBB0_760
	s_and_b64 vcc, exec, s[12:13]
	s_cbranch_vccz .LBB0_763
	s_barrier

.LBB0_784:
	ds_read_b128 v[144:147], v153
	ds_read_b128 v[156:159], v153 offset:1024
	ds_read_b128 v[160:163], v153 offset:2048
	ds_read_b128 v[164:167], v153 offset:3072
	ds_read_b128 v[168:171], v154
	ds_read_b128 v[172:175], v154 offset:1024
	ds_read_b128 v[176:179], v154 offset:2048
	ds_read_b128 v[180:183], v154 offset:3072
	s_add_u32 s26, s24, 0xfffe0080
	s_addc_u32 s27, s25, -1
	s_cmp_eq_u32 s56, 4
	s_cselect_b32 s29, s17, s27
	s_cselect_b32 s28, s52, s26
	s_cselect_b32 s27, s15, s55
	s_cselect_b32 s26, s53, s54
	v_lshl_add_u64 v[148:149], s[24:25], 0, v[138:139]
	s_add_i32 m0, s23, 0xc000
	ds_read_b128 v[184:187], v155
	ds_read_b128 v[188:191], v155 offset:1024
	ds_read_b128 v[192:195], v155 offset:2048
	ds_read_b128 v[196:199], v155 offset:3072
	ds_read_b128 v[200:203], v155 offset:4096
	ds_read_b128 v[204:207], v155 offset:5120
	ds_read_b128 v[208:211], v155 offset:6144
	ds_read_b128 v[212:215], v155 offset:7168
	global_load_lds_dwordx4 v[148:149], off
	v_lshl_add_u64 v[148:149], s[24:25], 0, v[136:137]
	s_add_i32 m0, s23, 0xe000
	s_nop 0
	global_load_lds_dwordx4 v[148:149], off
	s_waitcnt lgkmcnt(0)
	v_mfma_f32_16x16x32_bf16 v[124:127], v[144:147], v[184:187], v[124:127]
	s_waitcnt vmcnt(8)
	s_waitcnt lgkmcnt(0)
	s_barrier
	v_mfma_f32_16x16x32_bf16 v[120:123], v[160:163], v[184:187], v[120:123]
	v_mfma_f32_16x16x32_bf16 v[108:111], v[144:147], v[192:195], v[108:111]
	v_mfma_f32_16x16x32_bf16 v[104:107], v[160:163], v[192:195], v[104:107]
	v_mfma_f32_16x16x32_bf16 v[92:95], v[144:147], v[200:203], v[92:95]
	v_mfma_f32_16x16x32_bf16 v[88:91], v[160:163], v[200:203], v[88:91]
	v_mfma_f32_16x16x32_bf16 v[76:79], v[144:147], v[208:211], v[76:79]
	v_mfma_f32_16x16x32_bf16 v[72:75], v[160:163], v[208:211], v[72:75]
	v_mfma_f32_16x16x32_bf16 v[116:119], v[168:171], v[184:187], v[116:119]
	v_mfma_f32_16x16x32_bf16 v[112:115], v[176:179], v[184:187], v[112:115]
	v_mfma_f32_16x16x32_bf16 v[100:103], v[168:171], v[192:195], v[100:103]
	v_mfma_f32_16x16x32_bf16 v[96:99], v[176:179], v[192:195], v[96:99]
	v_mfma_f32_16x16x32_bf16 v[84:87], v[168:171], v[200:203], v[84:87]
	v_mfma_f32_16x16x32_bf16 v[80:83], v[176:179], v[200:203], v[80:83]
	v_mfma_f32_16x16x32_bf16 v[68:71], v[168:171], v[208:211], v[68:71]
	v_mfma_f32_16x16x32_bf16 v[64:67], v[176:179], v[208:211], v[64:67]
	v_mfma_f32_16x16x32_bf16 v[124:127], v[156:159], v[188:191], v[124:127]
	v_mfma_f32_16x16x32_bf16 v[120:123], v[164:167], v[188:191], v[120:123]
	v_mfma_f32_16x16x32_bf16 v[108:111], v[156:159], v[196:199], v[108:111]
	v_mfma_f32_16x16x32_bf16 v[104:107], v[164:167], v[196:199], v[104:107]
	v_mfma_f32_16x16x32_bf16 v[92:95], v[156:159], v[204:207], v[92:95]
	v_mfma_f32_16x16x32_bf16 v[88:91], v[164:167], v[204:207], v[88:91]
	v_mfma_f32_16x16x32_bf16 v[76:79], v[156:159], v[212:215], v[76:79]
	v_mfma_f32_16x16x32_bf16 v[72:75], v[164:167], v[212:215], v[72:75]
	v_mfma_f32_16x16x32_bf16 v[116:119], v[172:175], v[188:191], v[116:119]
	v_mfma_f32_16x16x32_bf16 v[112:115], v[180:183], v[188:191], v[112:115]
	v_mfma_f32_16x16x32_bf16 v[100:103], v[172:175], v[196:199], v[100:103]
	v_mfma_f32_16x16x32_bf16 v[96:99], v[180:183], v[196:199], v[96:99]
	v_mfma_f32_16x16x32_bf16 v[84:87], v[172:175], v[204:207], v[84:87]
	v_mfma_f32_16x16x32_bf16 v[80:83], v[180:183], v[204:207], v[80:83]
	v_mfma_f32_16x16x32_bf16 v[68:71], v[172:175], v[212:215], v[68:71]
	v_mfma_f32_16x16x32_bf16 v[64:67], v[180:183], v[212:215], v[64:67]
	s_barrier
	s_add_i32 s57, s49, s39
	v_lshl_add_u64 v[148:149], s[26:27], 0, v[130:131]
	s_mov_b32 m0, s57
	ds_read_b128 v[184:187], v155 offset:16384
	ds_read_b128 v[188:191], v155 offset:17408
	ds_read_b128 v[192:195], v155 offset:18432
	ds_read_b128 v[196:199], v155 offset:19456
	ds_read_b128 v[200:203], v155 offset:20480
	ds_read_b128 v[204:207], v155 offset:21504
	ds_read_b128 v[208:211], v155 offset:22528
	ds_read_b128 v[212:215], v155 offset:23552
	global_load_lds_dwordx4 v[148:149], off
	s_add_i32 m0, s57, 0x2000
	s_add_u32 s58, s26, 0x20000
	v_lshl_add_u64 v[216:217], s[26:27], 0, v[134:135]
	s_addc_u32 s59, s27, 0
	s_add_i32 s57, s50, s39
	global_load_lds_dwordx4 v[216:217], off
	v_lshl_add_u64 v[218:219], s[58:59], 0, v[130:131]
	s_mov_b32 m0, s57
	v_lshl_add_u64 v[220:221], s[28:29], 0, v[132:133]
	global_load_lds_dwordx4 v[218:219], off
	v_lshl_add_u64 v[218:219], s[58:59], 0, v[134:135]
	s_add_i32 m0, s57, 0x2000
	s_nop 0
	global_load_lds_dwordx4 v[218:219], off
	v_lshl_add_u64 v[218:219], s[28:29], 0, v[128:129]
	s_mov_b32 m0, s23
	s_nop 0
	global_load_lds_dwordx4 v[218:219], off
	s_mov_b32 m0, s40
	s_nop 0
	global_load_lds_dwordx4 v[220:221], off
	s_waitcnt lgkmcnt(0)
	v_mfma_f32_16x16x32_bf16 v[60:63], v[144:147], v[184:187], v[60:63]
	s_waitcnt vmcnt(8)
	s_waitcnt lgkmcnt(0)
	s_barrier
	v_mfma_f32_16x16x32_bf16 v[56:59], v[160:163], v[184:187], v[56:59]
	v_mfma_f32_16x16x32_bf16 v[44:47], v[144:147], v[192:195], v[44:47]
	v_mfma_f32_16x16x32_bf16 v[40:43], v[160:163], v[192:195], v[40:43]
	v_mfma_f32_16x16x32_bf16 v[28:31], v[144:147], v[200:203], v[28:31]
	v_mfma_f32_16x16x32_bf16 v[24:27], v[160:163], v[200:203], v[24:27]
	v_mfma_f32_16x16x32_bf16 v[12:15], v[144:147], v[208:211], v[12:15]
	v_mfma_f32_16x16x32_bf16 v[8:11], v[160:163], v[208:211], v[8:11]
	v_mfma_f32_16x16x32_bf16 v[52:55], v[168:171], v[184:187], v[52:55]
	v_mfma_f32_16x16x32_bf16 v[48:51], v[176:179], v[184:187], v[48:51]
	v_mfma_f32_16x16x32_bf16 v[36:39], v[168:171], v[192:195], v[36:39]
	v_mfma_f32_16x16x32_bf16 v[32:35], v[176:179], v[192:195], v[32:35]
	v_mfma_f32_16x16x32_bf16 v[20:23], v[168:171], v[200:203], v[20:23]
	v_mfma_f32_16x16x32_bf16 v[16:19], v[176:179], v[200:203], v[16:19]
	v_mfma_f32_16x16x32_bf16 v[4:7], v[168:171], v[208:211], v[4:7]
	v_mfma_f32_16x16x32_bf16 v[0:3], v[176:179], v[208:211], v[0:3]
	v_mfma_f32_16x16x32_bf16 v[60:63], v[156:159], v[188:191], v[60:63]
	v_mfma_f32_16x16x32_bf16 v[56:59], v[164:167], v[188:191], v[56:59]
	v_mfma_f32_16x16x32_bf16 v[44:47], v[156:159], v[196:199], v[44:47]
	v_mfma_f32_16x16x32_bf16 v[40:43], v[164:167], v[196:199], v[40:43]
	v_mfma_f32_16x16x32_bf16 v[28:31], v[156:159], v[204:207], v[28:31]
	v_mfma_f32_16x16x32_bf16 v[24:27], v[164:167], v[204:207], v[24:27]
	v_mfma_f32_16x16x32_bf16 v[12:15], v[156:159], v[212:215], v[12:15]
	v_mfma_f32_16x16x32_bf16 v[8:11], v[164:167], v[212:215], v[8:11]
	v_mfma_f32_16x16x32_bf16 v[52:55], v[172:175], v[188:191], v[52:55]
	v_mfma_f32_16x16x32_bf16 v[48:51], v[180:183], v[188:191], v[48:51]
	v_mfma_f32_16x16x32_bf16 v[36:39], v[172:175], v[196:199], v[36:39]
	v_mfma_f32_16x16x32_bf16 v[32:35], v[180:183], v[196:199], v[32:35]
	v_mfma_f32_16x16x32_bf16 v[20:23], v[172:175], v[204:207], v[20:23]
	v_mfma_f32_16x16x32_bf16 v[16:19], v[180:183], v[204:207], v[16:19]
	v_mfma_f32_16x16x32_bf16 v[4:7], v[172:175], v[212:215], v[4:7]
	v_mfma_f32_16x16x32_bf16 v[0:3], v[180:183], v[212:215], v[0:3]
	s_barrier
	s_add_i32 s57, 0, 0x18000
	s_add_i32 s58, 0, 0x1c000
	v_add_u32_e32 v164, s57, v152
	v_add_u32_e32 v180, s58, v152
	ds_read_b128 v[144:147], v164
	ds_read_b128 v[156:159], v164 offset:1024
	ds_read_b128 v[160:163], v164 offset:2048
	ds_read_b128 v[164:167], v164 offset:3072
	ds_read_b128 v[168:171], v180
	ds_read_b128 v[172:175], v180 offset:1024
	ds_read_b128 v[176:179], v180 offset:2048
	ds_read_b128 v[180:183], v180 offset:3072
	s_add_u32 s28, s28, 0x20000
	s_addc_u32 s29, s29, 0
	s_mov_b32 m0, s41
	v_lshl_add_u64 v[222:223], s[28:29], 0, v[128:129]
	ds_read_b128 v[184:187], v155 offset:32768
	ds_read_b128 v[188:191], v155 offset:33792
	ds_read_b128 v[192:195], v155 offset:34816
	ds_read_b128 v[196:199], v155 offset:35840
	ds_read_b128 v[200:203], v155 offset:36864
	ds_read_b128 v[204:207], v155 offset:37888
	ds_read_b128 v[208:211], v155 offset:38912
	ds_read_b128 v[212:215], v155 offset:39936
	global_load_lds_dwordx4 v[222:223], off
	v_lshl_add_u64 v[222:223], s[28:29], 0, v[132:133]
	s_mov_b32 m0, s42
	s_nop 0
	global_load_lds_dwordx4 v[222:223], off
	s_waitcnt lgkmcnt(0)
	v_mfma_f32_16x16x32_bf16 v[124:127], v[144:147], v[184:187], v[124:127]
	s_waitcnt vmcnt(8)
	s_waitcnt lgkmcnt(0)
	s_barrier
	v_mfma_f32_16x16x32_bf16 v[120:123], v[160:163], v[184:187], v[120:123]
	v_mfma_f32_16x16x32_bf16 v[108:111], v[144:147], v[192:195], v[108:111]
	v_mfma_f32_16x16x32_bf16 v[104:107], v[160:163], v[192:195], v[104:107]
	v_mfma_f32_16x16x32_bf16 v[92:95], v[144:147], v[200:203], v[92:95]
	v_mfma_f32_16x16x32_bf16 v[88:91], v[160:163], v[200:203], v[88:91]
	v_mfma_f32_16x16x32_bf16 v[76:79], v[144:147], v[208:211], v[76:79]
	v_mfma_f32_16x16x32_bf16 v[72:75], v[160:163], v[208:211], v[72:75]
	v_mfma_f32_16x16x32_bf16 v[116:119], v[168:171], v[184:187], v[116:119]
	v_mfma_f32_16x16x32_bf16 v[112:115], v[176:179], v[184:187], v[112:115]
	v_mfma_f32_16x16x32_bf16 v[100:103], v[168:171], v[192:195], v[100:103]
	v_mfma_f32_16x16x32_bf16 v[96:99], v[176:179], v[192:195], v[96:99]
	v_mfma_f32_16x16x32_bf16 v[84:87], v[168:171], v[200:203], v[84:87]
	v_mfma_f32_16x16x32_bf16 v[80:83], v[176:179], v[200:203], v[80:83]
	v_mfma_f32_16x16x32_bf16 v[68:71], v[168:171], v[208:211], v[68:71]
	v_mfma_f32_16x16x32_bf16 v[64:67], v[176:179], v[208:211], v[64:67]
	v_mfma_f32_16x16x32_bf16 v[124:127], v[156:159], v[188:191], v[124:127]
	v_mfma_f32_16x16x32_bf16 v[120:123], v[164:167], v[188:191], v[120:123]
	v_mfma_f32_16x16x32_bf16 v[108:111], v[156:159], v[196:199], v[108:111]
	v_mfma_f32_16x16x32_bf16 v[104:107], v[164:167], v[196:199], v[104:107]
	v_mfma_f32_16x16x32_bf16 v[92:95], v[156:159], v[204:207], v[92:95]
	v_mfma_f32_16x16x32_bf16 v[88:91], v[164:167], v[204:207], v[88:91]
	v_mfma_f32_16x16x32_bf16 v[76:79], v[156:159], v[212:215], v[76:79]
	v_mfma_f32_16x16x32_bf16 v[72:75], v[164:167], v[212:215], v[72:75]
	v_mfma_f32_16x16x32_bf16 v[116:119], v[172:175], v[188:191], v[116:119]
	v_mfma_f32_16x16x32_bf16 v[112:115], v[180:183], v[188:191], v[112:115]
	v_mfma_f32_16x16x32_bf16 v[100:103], v[172:175], v[196:199], v[100:103]
	v_mfma_f32_16x16x32_bf16 v[96:99], v[180:183], v[196:199], v[96:99]
	v_mfma_f32_16x16x32_bf16 v[84:87], v[172:175], v[204:207], v[84:87]
	v_mfma_f32_16x16x32_bf16 v[80:83], v[180:183], v[204:207], v[80:83]
	v_mfma_f32_16x16x32_bf16 v[68:71], v[172:175], v[212:215], v[68:71]
	v_mfma_f32_16x16x32_bf16 v[64:67], v[180:183], v[212:215], v[64:67]
	s_barrier
	s_add_i32 s28, s57, s39
	v_lshl_add_u64 v[148:149], v[148:149], 0, s[10:11]
	s_mov_b32 m0, s28
	ds_read_b128 v[184:187], v155 offset:49152
	ds_read_b128 v[188:191], v155 offset:50176
	ds_read_b128 v[192:195], v155 offset:51200
	ds_read_b128 v[196:199], v155 offset:52224
	ds_read_b128 v[200:203], v155 offset:53248
	ds_read_b128 v[204:207], v155 offset:54272
	ds_read_b128 v[208:211], v155 offset:55296
	ds_read_b128 v[212:215], v155 offset:56320
	global_load_lds_dwordx4 v[148:149], off
	s_add_i32 m0, s28, 0x2000
	s_add_u32 s26, s26, 0x20080
	v_lshl_add_u64 v[148:149], v[216:217], 0, s[10:11]
	s_addc_u32 s27, s27, 0
	s_add_i32 s28, s58, s39
	global_load_lds_dwordx4 v[148:149], off
	v_lshl_add_u64 v[148:149], s[26:27], 0, v[130:131]
	s_mov_b32 m0, s28
	s_nop 0
	global_load_lds_dwordx4 v[148:149], off
	v_lshl_add_u64 v[148:149], s[26:27], 0, v[134:135]
	s_add_i32 m0, s28, 0x2000
	s_nop 0
	global_load_lds_dwordx4 v[148:149], off
	v_lshl_add_u64 v[148:149], v[218:219], 0, s[10:11]
	s_mov_b32 m0, s46
	s_nop 0
	global_load_lds_dwordx4 v[148:149], off
	v_lshl_add_u64 v[148:149], v[220:221], 0, s[10:11]
	s_mov_b32 m0, s47
	s_nop 0
	global_load_lds_dwordx4 v[148:149], off
	s_waitcnt lgkmcnt(0)
	v_mfma_f32_16x16x32_bf16 v[60:63], v[144:147], v[184:187], v[60:63]
	s_waitcnt vmcnt(8)
	s_waitcnt lgkmcnt(0)
	s_barrier
	v_mfma_f32_16x16x32_bf16 v[56:59], v[160:163], v[184:187], v[56:59]
	v_mfma_f32_16x16x32_bf16 v[44:47], v[144:147], v[192:195], v[44:47]
	v_mfma_f32_16x16x32_bf16 v[40:43], v[160:163], v[192:195], v[40:43]
	v_mfma_f32_16x16x32_bf16 v[28:31], v[144:147], v[200:203], v[28:31]
	v_mfma_f32_16x16x32_bf16 v[24:27], v[160:163], v[200:203], v[24:27]
	v_mfma_f32_16x16x32_bf16 v[12:15], v[144:147], v[208:211], v[12:15]
	v_mfma_f32_16x16x32_bf16 v[8:11], v[160:163], v[208:211], v[8:11]
	v_mfma_f32_16x16x32_bf16 v[52:55], v[168:171], v[184:187], v[52:55]
	v_mfma_f32_16x16x32_bf16 v[48:51], v[176:179], v[184:187], v[48:51]
	v_mfma_f32_16x16x32_bf16 v[36:39], v[168:171], v[192:195], v[36:39]
	v_mfma_f32_16x16x32_bf16 v[32:35], v[176:179], v[192:195], v[32:35]
	v_mfma_f32_16x16x32_bf16 v[20:23], v[168:171], v[200:203], v[20:23]
	v_mfma_f32_16x16x32_bf16 v[16:19], v[176:179], v[200:203], v[16:19]
	v_mfma_f32_16x16x32_bf16 v[4:7], v[168:171], v[208:211], v[4:7]
	v_mfma_f32_16x16x32_bf16 v[0:3], v[176:179], v[208:211], v[0:3]
	v_mfma_f32_16x16x32_bf16 v[60:63], v[156:159], v[188:191], v[60:63]
	v_mfma_f32_16x16x32_bf16 v[56:59], v[164:167], v[188:191], v[56:59]
	v_mfma_f32_16x16x32_bf16 v[44:47], v[156:159], v[196:199], v[44:47]
	v_mfma_f32_16x16x32_bf16 v[40:43], v[164:167], v[196:199], v[40:43]
	v_mfma_f32_16x16x32_bf16 v[28:31], v[156:159], v[204:207], v[28:31]
	v_mfma_f32_16x16x32_bf16 v[24:27], v[164:167], v[204:207], v[24:27]
	v_mfma_f32_16x16x32_bf16 v[12:15], v[156:159], v[212:215], v[12:15]
	v_mfma_f32_16x16x32_bf16 v[8:11], v[164:167], v[212:215], v[8:11]
	v_mfma_f32_16x16x32_bf16 v[52:55], v[172:175], v[188:191], v[52:55]
	v_mfma_f32_16x16x32_bf16 v[48:51], v[180:183], v[188:191], v[48:51]
	v_mfma_f32_16x16x32_bf16 v[36:39], v[172:175], v[196:199], v[36:39]
	v_mfma_f32_16x16x32_bf16 v[32:35], v[180:183], v[196:199], v[32:35]
	v_mfma_f32_16x16x32_bf16 v[20:23], v[172:175], v[204:207], v[20:23]
	v_mfma_f32_16x16x32_bf16 v[16:19], v[180:183], v[204:207], v[16:19]
	v_mfma_f32_16x16x32_bf16 v[4:7], v[172:175], v[212:215], v[4:7]
	v_mfma_f32_16x16x32_bf16 v[0:3], v[180:183], v[212:215], v[0:3]
	s_barrier
	s_add_i32 s56, s56, 2
	s_add_u32 s54, s54, 0x100
	s_addc_u32 s55, s55, 0
	s_add_u32 s24, s24, 0x100
	s_addc_u32 s25, s25, 0
	s_cmp_gt_u32 s56, 5
	s_cbranch_scc0 .LBB0_784
	s_and_b64 vcc, exec, s[12:13]
	s_cbranch_vccz .LBB0_787
	s_barrier

.LBB0_854:
	ds_read_b128 v[128:131], v225
	ds_read_b128 v[132:135], v225 offset:1024
	ds_read_b128 v[136:139], v225 offset:2048
	ds_read_b128 v[140:143], v225 offset:3072
	ds_read_b128 v[160:163], v226
	ds_read_b128 v[164:167], v226 offset:1024
	ds_read_b128 v[168:171], v226 offset:2048
	ds_read_b128 v[172:175], v226 offset:3072
	s_add_u32 s30, s28, 0xfffc0080
	s_addc_u32 s31, s29, -1
	s_cmp_eq_u32 s64, 12
	s_cselect_b32 s35, s19, s31
	s_cselect_b32 s34, s25, s30
	s_cselect_b32 s31, s17, s63
	s_cselect_b32 s30, s27, s62
	v_lshl_add_u64 v[208:209], s[28:29], 0, v[154:155]
	s_add_i32 m0, s43, 0xc000
	ds_read_b128 v[176:179], v227
	ds_read_b128 v[180:183], v227 offset:1024
	ds_read_b128 v[184:187], v227 offset:2048
	ds_read_b128 v[188:191], v227 offset:3072
	ds_read_b128 v[192:195], v227 offset:4096
	ds_read_b128 v[196:199], v227 offset:5120
	ds_read_b128 v[200:203], v227 offset:6144
	ds_read_b128 v[204:207], v227 offset:7168
	global_load_lds_dwordx4 v[208:209], off
	v_lshl_add_u64 v[208:209], s[28:29], 0, v[152:153]
	s_add_i32 m0, s43, 0xe000
	s_nop 0
	global_load_lds_dwordx4 v[208:209], off
	s_waitcnt lgkmcnt(0)
	v_mfma_f32_16x16x32_bf16 v[124:127], v[128:131], v[176:179], v[124:127]
	s_waitcnt vmcnt(8)
	s_waitcnt lgkmcnt(0)
	s_barrier
	v_mfma_f32_16x16x32_bf16 v[120:123], v[136:139], v[176:179], v[120:123]
	v_mfma_f32_16x16x32_bf16 v[116:119], v[128:131], v[184:187], v[116:119]
	v_mfma_f32_16x16x32_bf16 v[112:115], v[136:139], v[184:187], v[112:115]
	v_mfma_f32_16x16x32_bf16 v[108:111], v[128:131], v[192:195], v[108:111]
	v_mfma_f32_16x16x32_bf16 v[104:107], v[136:139], v[192:195], v[104:107]
	v_mfma_f32_16x16x32_bf16 v[100:103], v[128:131], v[200:203], v[100:103]
	v_mfma_f32_16x16x32_bf16 v[96:99], v[136:139], v[200:203], v[96:99]
	v_mfma_f32_16x16x32_bf16 v[60:63], v[160:163], v[176:179], v[60:63]
	v_mfma_f32_16x16x32_bf16 v[56:59], v[168:171], v[176:179], v[56:59]
	v_mfma_f32_16x16x32_bf16 v[52:55], v[160:163], v[184:187], v[52:55]
	v_mfma_f32_16x16x32_bf16 v[48:51], v[168:171], v[184:187], v[48:51]
	v_mfma_f32_16x16x32_bf16 v[44:47], v[160:163], v[192:195], v[44:47]
	v_mfma_f32_16x16x32_bf16 v[40:43], v[168:171], v[192:195], v[40:43]
	v_mfma_f32_16x16x32_bf16 v[36:39], v[160:163], v[200:203], v[36:39]
	v_mfma_f32_16x16x32_bf16 v[32:35], v[168:171], v[200:203], v[32:35]
	v_mfma_f32_16x16x32_bf16 v[124:127], v[132:135], v[180:183], v[124:127]
	v_mfma_f32_16x16x32_bf16 v[120:123], v[140:143], v[180:183], v[120:123]
	v_mfma_f32_16x16x32_bf16 v[116:119], v[132:135], v[188:191], v[116:119]
	v_mfma_f32_16x16x32_bf16 v[112:115], v[140:143], v[188:191], v[112:115]
	v_mfma_f32_16x16x32_bf16 v[108:111], v[132:135], v[196:199], v[108:111]
	v_mfma_f32_16x16x32_bf16 v[104:107], v[140:143], v[196:199], v[104:107]
	v_mfma_f32_16x16x32_bf16 v[100:103], v[132:135], v[204:207], v[100:103]
	v_mfma_f32_16x16x32_bf16 v[96:99], v[140:143], v[204:207], v[96:99]
	v_mfma_f32_16x16x32_bf16 v[60:63], v[164:167], v[180:183], v[60:63]
	v_mfma_f32_16x16x32_bf16 v[56:59], v[172:175], v[180:183], v[56:59]
	v_mfma_f32_16x16x32_bf16 v[52:55], v[164:167], v[188:191], v[52:55]
	v_mfma_f32_16x16x32_bf16 v[48:51], v[172:175], v[188:191], v[48:51]
	v_mfma_f32_16x16x32_bf16 v[44:47], v[164:167], v[196:199], v[44:47]
	v_mfma_f32_16x16x32_bf16 v[40:43], v[172:175], v[196:199], v[40:43]
	v_mfma_f32_16x16x32_bf16 v[36:39], v[164:167], v[204:207], v[36:39]
	v_mfma_f32_16x16x32_bf16 v[32:35], v[172:175], v[204:207], v[32:35]
	s_barrier
	s_add_i32 s65, s60, s42
	v_lshl_add_u64 v[208:209], s[30:31], 0, v[146:147]
	s_mov_b32 m0, s65
	ds_read_b128 v[176:179], v227 offset:16384
	ds_read_b128 v[180:183], v227 offset:17408
	ds_read_b128 v[184:187], v227 offset:18432
	ds_read_b128 v[188:191], v227 offset:19456
	ds_read_b128 v[192:195], v227 offset:20480
	ds_read_b128 v[196:199], v227 offset:21504
	ds_read_b128 v[200:203], v227 offset:22528
	ds_read_b128 v[204:207], v227 offset:23552
	global_load_lds_dwordx4 v[208:209], off
	s_add_i32 m0, s65, 0x2000
	s_add_u32 s66, s30, 0x40000
	v_lshl_add_u64 v[210:211], s[30:31], 0, v[150:151]
	s_addc_u32 s67, s31, 0
	s_add_i32 s65, s61, s42
	global_load_lds_dwordx4 v[210:211], off
	v_lshl_add_u64 v[212:213], s[66:67], 0, v[146:147]
	s_mov_b32 m0, s65
	v_lshl_add_u64 v[214:215], s[34:35], 0, v[148:149]
	global_load_lds_dwordx4 v[212:213], off
	v_lshl_add_u64 v[212:213], s[66:67], 0, v[150:151]
	s_add_i32 m0, s65, 0x2000
	s_nop 0
	global_load_lds_dwordx4 v[212:213], off
	v_lshl_add_u64 v[212:213], s[34:35], 0, v[144:145]
	s_mov_b32 m0, s43
	s_nop 0
	global_load_lds_dwordx4 v[212:213], off
	s_mov_b32 m0, s44
	s_nop 0
	global_load_lds_dwordx4 v[214:215], off
	s_waitcnt lgkmcnt(0)
	v_mfma_f32_16x16x32_bf16 v[92:95], v[128:131], v[176:179], v[92:95]
	s_waitcnt vmcnt(8)
	s_waitcnt lgkmcnt(0)
	s_barrier
	v_mfma_f32_16x16x32_bf16 v[88:91], v[136:139], v[176:179], v[88:91]
	v_mfma_f32_16x16x32_bf16 v[84:87], v[128:131], v[184:187], v[84:87]
	v_mfma_f32_16x16x32_bf16 v[80:83], v[136:139], v[184:187], v[80:83]
	v_mfma_f32_16x16x32_bf16 v[76:79], v[128:131], v[192:195], v[76:79]
	v_mfma_f32_16x16x32_bf16 v[72:75], v[136:139], v[192:195], v[72:75]
	v_mfma_f32_16x16x32_bf16 v[68:71], v[128:131], v[200:203], v[68:71]
	v_mfma_f32_16x16x32_bf16 v[64:67], v[136:139], v[200:203], v[64:67]
	v_mfma_f32_16x16x32_bf16 v[28:31], v[160:163], v[176:179], v[28:31]
	v_mfma_f32_16x16x32_bf16 v[24:27], v[168:171], v[176:179], v[24:27]
	v_mfma_f32_16x16x32_bf16 v[20:23], v[160:163], v[184:187], v[20:23]
	v_mfma_f32_16x16x32_bf16 v[16:19], v[168:171], v[184:187], v[16:19]
	v_mfma_f32_16x16x32_bf16 v[12:15], v[160:163], v[192:195], v[12:15]
	v_mfma_f32_16x16x32_bf16 v[8:11], v[168:171], v[192:195], v[8:11]
	v_mfma_f32_16x16x32_bf16 v[4:7], v[160:163], v[200:203], v[4:7]
	v_mfma_f32_16x16x32_bf16 v[0:3], v[168:171], v[200:203], v[0:3]
	v_mfma_f32_16x16x32_bf16 v[92:95], v[132:135], v[180:183], v[92:95]
	v_mfma_f32_16x16x32_bf16 v[88:91], v[140:143], v[180:183], v[88:91]
	v_mfma_f32_16x16x32_bf16 v[84:87], v[132:135], v[188:191], v[84:87]
	v_mfma_f32_16x16x32_bf16 v[80:83], v[140:143], v[188:191], v[80:83]
	v_mfma_f32_16x16x32_bf16 v[76:79], v[132:135], v[196:199], v[76:79]
	v_mfma_f32_16x16x32_bf16 v[72:75], v[140:143], v[196:199], v[72:75]
	v_mfma_f32_16x16x32_bf16 v[68:71], v[132:135], v[204:207], v[68:71]
	v_mfma_f32_16x16x32_bf16 v[64:67], v[140:143], v[204:207], v[64:67]
	v_mfma_f32_16x16x32_bf16 v[28:31], v[164:167], v[180:183], v[28:31]
	v_mfma_f32_16x16x32_bf16 v[24:27], v[172:175], v[180:183], v[24:27]
	v_mfma_f32_16x16x32_bf16 v[20:23], v[164:167], v[188:191], v[20:23]
	v_mfma_f32_16x16x32_bf16 v[16:19], v[172:175], v[188:191], v[16:19]
	v_mfma_f32_16x16x32_bf16 v[12:15], v[164:167], v[196:199], v[12:15]
	v_mfma_f32_16x16x32_bf16 v[8:11], v[172:175], v[196:199], v[8:11]
	v_mfma_f32_16x16x32_bf16 v[4:7], v[164:167], v[204:207], v[4:7]
	v_mfma_f32_16x16x32_bf16 v[0:3], v[172:175], v[204:207], v[0:3]
	s_barrier
	s_add_i32 s65, 0, 0x18000
	s_add_i32 s66, 0, 0x1c000
	v_add_u32_e32 v140, s65, v224
	v_add_u32_e32 v172, s66, v224
	ds_read_b128 v[128:131], v140
	ds_read_b128 v[132:135], v140 offset:1024
	ds_read_b128 v[136:139], v140 offset:2048
	ds_read_b128 v[140:143], v140 offset:3072
	ds_read_b128 v[160:163], v172
	ds_read_b128 v[164:167], v172 offset:1024
	ds_read_b128 v[168:171], v172 offset:2048
	ds_read_b128 v[172:175], v172 offset:3072
	s_add_u32 s34, s34, 0x40000
	s_addc_u32 s35, s35, 0
	s_mov_b32 m0, s45
	v_lshl_add_u64 v[216:217], s[34:35], 0, v[144:145]
	ds_read_b128 v[176:179], v227 offset:32768
	ds_read_b128 v[180:183], v227 offset:33792
	ds_read_b128 v[184:187], v227 offset:34816
	ds_read_b128 v[188:191], v227 offset:35840
	ds_read_b128 v[192:195], v227 offset:36864
	ds_read_b128 v[196:199], v227 offset:37888
	ds_read_b128 v[200:203], v227 offset:38912
	ds_read_b128 v[204:207], v227 offset:39936
	global_load_lds_dwordx4 v[216:217], off
	v_lshl_add_u64 v[216:217], s[34:35], 0, v[148:149]
	s_mov_b32 m0, s46
	s_nop 0
	global_load_lds_dwordx4 v[216:217], off
	s_waitcnt lgkmcnt(0)
	v_mfma_f32_16x16x32_bf16 v[124:127], v[128:131], v[176:179], v[124:127]
	s_waitcnt vmcnt(8)
	s_waitcnt lgkmcnt(0)
	s_barrier
	v_mfma_f32_16x16x32_bf16 v[120:123], v[136:139], v[176:179], v[120:123]
	v_mfma_f32_16x16x32_bf16 v[116:119], v[128:131], v[184:187], v[116:119]
	v_mfma_f32_16x16x32_bf16 v[112:115], v[136:139], v[184:187], v[112:115]
	v_mfma_f32_16x16x32_bf16 v[108:111], v[128:131], v[192:195], v[108:111]
	v_mfma_f32_16x16x32_bf16 v[104:107], v[136:139], v[192:195], v[104:107]
	v_mfma_f32_16x16x32_bf16 v[100:103], v[128:131], v[200:203], v[100:103]
	v_mfma_f32_16x16x32_bf16 v[96:99], v[136:139], v[200:203], v[96:99]
	v_mfma_f32_16x16x32_bf16 v[60:63], v[160:163], v[176:179], v[60:63]
	v_mfma_f32_16x16x32_bf16 v[56:59], v[168:171], v[176:179], v[56:59]
	v_mfma_f32_16x16x32_bf16 v[52:55], v[160:163], v[184:187], v[52:55]
	v_mfma_f32_16x16x32_bf16 v[48:51], v[168:171], v[184:187], v[48:51]
	v_mfma_f32_16x16x32_bf16 v[44:47], v[160:163], v[192:195], v[44:47]
	v_mfma_f32_16x16x32_bf16 v[40:43], v[168:171], v[192:195], v[40:43]
	v_mfma_f32_16x16x32_bf16 v[36:39], v[160:163], v[200:203], v[36:39]
	v_mfma_f32_16x16x32_bf16 v[32:35], v[168:171], v[200:203], v[32:35]
	v_mfma_f32_16x16x32_bf16 v[124:127], v[132:135], v[180:183], v[124:127]
	v_mfma_f32_16x16x32_bf16 v[120:123], v[140:143], v[180:183], v[120:123]
	v_mfma_f32_16x16x32_bf16 v[116:119], v[132:135], v[188:191], v[116:119]
	v_mfma_f32_16x16x32_bf16 v[112:115], v[140:143], v[188:191], v[112:115]
	v_mfma_f32_16x16x32_bf16 v[108:111], v[132:135], v[196:199], v[108:111]
	v_mfma_f32_16x16x32_bf16 v[104:107], v[140:143], v[196:199], v[104:107]
	v_mfma_f32_16x16x32_bf16 v[100:103], v[132:135], v[204:207], v[100:103]
	v_mfma_f32_16x16x32_bf16 v[96:99], v[140:143], v[204:207], v[96:99]
	v_mfma_f32_16x16x32_bf16 v[60:63], v[164:167], v[180:183], v[60:63]
	v_mfma_f32_16x16x32_bf16 v[56:59], v[172:175], v[180:183], v[56:59]
	v_mfma_f32_16x16x32_bf16 v[52:55], v[164:167], v[188:191], v[52:55]
	v_mfma_f32_16x16x32_bf16 v[48:51], v[172:175], v[188:191], v[48:51]
	v_mfma_f32_16x16x32_bf16 v[44:47], v[164:167], v[196:199], v[44:47]
	v_mfma_f32_16x16x32_bf16 v[40:43], v[172:175], v[196:199], v[40:43]
	v_mfma_f32_16x16x32_bf16 v[36:39], v[164:167], v[204:207], v[36:39]
	v_mfma_f32_16x16x32_bf16 v[32:35], v[172:175], v[204:207], v[32:35]
	s_barrier
	s_add_i32 s34, s65, s42
	v_lshl_add_u64 v[208:209], v[208:209], 0, s[12:13]
	s_mov_b32 m0, s34
	ds_read_b128 v[176:179], v227 offset:49152
	ds_read_b128 v[180:183], v227 offset:50176
	ds_read_b128 v[184:187], v227 offset:51200
	ds_read_b128 v[188:191], v227 offset:52224
	ds_read_b128 v[192:195], v227 offset:53248
	ds_read_b128 v[196:199], v227 offset:54272
	ds_read_b128 v[200:203], v227 offset:55296
	ds_read_b128 v[204:207], v227 offset:56320
	global_load_lds_dwordx4 v[208:209], off
	s_add_i32 m0, s34, 0x2000
	s_add_u32 s30, s30, 0x40080
	v_lshl_add_u64 v[208:209], v[210:211], 0, s[12:13]
	s_addc_u32 s31, s31, 0
	s_add_i32 s34, s66, s42
	global_load_lds_dwordx4 v[208:209], off
	v_lshl_add_u64 v[208:209], s[30:31], 0, v[146:147]
	s_mov_b32 m0, s34
	s_nop 0
	global_load_lds_dwordx4 v[208:209], off
	v_lshl_add_u64 v[208:209], s[30:31], 0, v[150:151]
	s_add_i32 m0, s34, 0x2000
	s_nop 0
	global_load_lds_dwordx4 v[208:209], off
	v_lshl_add_u64 v[208:209], v[212:213], 0, s[12:13]
	s_mov_b32 m0, s54
	s_nop 0
	global_load_lds_dwordx4 v[208:209], off
	v_lshl_add_u64 v[208:209], v[214:215], 0, s[12:13]
	s_mov_b32 m0, s55
	s_nop 0
	global_load_lds_dwordx4 v[208:209], off
	s_waitcnt lgkmcnt(0)
	v_mfma_f32_16x16x32_bf16 v[92:95], v[128:131], v[176:179], v[92:95]
	s_waitcnt vmcnt(8)
	s_waitcnt lgkmcnt(0)
	s_barrier
	v_mfma_f32_16x16x32_bf16 v[88:91], v[136:139], v[176:179], v[88:91]
	v_mfma_f32_16x16x32_bf16 v[84:87], v[128:131], v[184:187], v[84:87]
	v_mfma_f32_16x16x32_bf16 v[80:83], v[136:139], v[184:187], v[80:83]
	v_mfma_f32_16x16x32_bf16 v[76:79], v[128:131], v[192:195], v[76:79]
	v_mfma_f32_16x16x32_bf16 v[72:75], v[136:139], v[192:195], v[72:75]
	v_mfma_f32_16x16x32_bf16 v[68:71], v[128:131], v[200:203], v[68:71]
	v_mfma_f32_16x16x32_bf16 v[64:67], v[136:139], v[200:203], v[64:67]
	v_mfma_f32_16x16x32_bf16 v[28:31], v[160:163], v[176:179], v[28:31]
	v_mfma_f32_16x16x32_bf16 v[24:27], v[168:171], v[176:179], v[24:27]
	v_mfma_f32_16x16x32_bf16 v[20:23], v[160:163], v[184:187], v[20:23]
	v_mfma_f32_16x16x32_bf16 v[16:19], v[168:171], v[184:187], v[16:19]
	v_mfma_f32_16x16x32_bf16 v[12:15], v[160:163], v[192:195], v[12:15]
	v_mfma_f32_16x16x32_bf16 v[8:11], v[168:171], v[192:195], v[8:11]
	v_mfma_f32_16x16x32_bf16 v[4:7], v[160:163], v[200:203], v[4:7]
	v_mfma_f32_16x16x32_bf16 v[0:3], v[168:171], v[200:203], v[0:3]
	v_mfma_f32_16x16x32_bf16 v[92:95], v[132:135], v[180:183], v[92:95]
	v_mfma_f32_16x16x32_bf16 v[88:91], v[140:143], v[180:183], v[88:91]
	v_mfma_f32_16x16x32_bf16 v[84:87], v[132:135], v[188:191], v[84:87]
	v_mfma_f32_16x16x32_bf16 v[80:83], v[140:143], v[188:191], v[80:83]
	v_mfma_f32_16x16x32_bf16 v[76:79], v[132:135], v[196:199], v[76:79]
	v_mfma_f32_16x16x32_bf16 v[72:75], v[140:143], v[196:199], v[72:75]
	v_mfma_f32_16x16x32_bf16 v[68:71], v[132:135], v[204:207], v[68:71]
	v_mfma_f32_16x16x32_bf16 v[64:67], v[140:143], v[204:207], v[64:67]
	v_mfma_f32_16x16x32_bf16 v[28:31], v[164:167], v[180:183], v[28:31]
	v_mfma_f32_16x16x32_bf16 v[24:27], v[172:175], v[180:183], v[24:27]
	v_mfma_f32_16x16x32_bf16 v[20:23], v[164:167], v[188:191], v[20:23]
	v_mfma_f32_16x16x32_bf16 v[16:19], v[172:175], v[188:191], v[16:19]
	v_mfma_f32_16x16x32_bf16 v[12:15], v[164:167], v[196:199], v[12:15]
	v_mfma_f32_16x16x32_bf16 v[8:11], v[172:175], v[196:199], v[8:11]
	v_mfma_f32_16x16x32_bf16 v[4:7], v[164:167], v[204:207], v[4:7]
	v_mfma_f32_16x16x32_bf16 v[0:3], v[172:175], v[204:207], v[0:3]
	s_barrier
	s_add_i32 s64, s64, 2
	s_add_u32 s62, s62, 0x100
	s_addc_u32 s63, s63, 0
	s_add_u32 s28, s28, 0x100
	s_addc_u32 s29, s29, 0
	s_cmp_gt_u32 s64, 13
	s_cbranch_scc0 .LBB0_854
	s_and_b64 vcc, exec, s[14:15]
	s_cbranch_vccz .LBB0_857
	s_barrier

.LBB0_930:
	ds_read_b128 v[128:131], v173
	ds_read_b128 v[132:135], v173 offset:1024
	ds_read_b128 v[152:155], v173 offset:2048
	ds_read_b128 v[158:161], v173 offset:3072
	ds_read_b128 v[164:167], v177
	ds_read_b128 v[180:183], v177 offset:1024
	ds_read_b128 v[186:189], v177 offset:2048
	ds_read_b128 v[190:193], v177 offset:3072
	s_add_u32 s34, s6, 0xfffc0080
	s_addc_u32 s35, s7, -1
	s_cmp_eq_u32 s64, 12
	s_cselect_b32 s37, s27, s35
	s_cselect_b32 s36, s60, s34
	s_cselect_b32 s35, s25, s63
	s_cselect_b32 s34, s61, s62
	v_lshl_add_u64 v[170:171], s[6:7], 0, v[146:147]
	s_add_i32 m0, s43, 0xc000
	ds_read_b128 v[194:197], v179
	ds_read_b128 v[198:201], v179 offset:1024
	ds_read_b128 v[202:205], v179 offset:2048
	ds_read_b128 v[206:209], v179 offset:3072
	ds_read_b128 v[210:213], v179 offset:4096
	ds_read_b128 v[214:217], v179 offset:5120
	ds_read_b128 v[218:221], v179 offset:6144
	ds_read_b128 v[222:225], v179 offset:7168
	global_load_lds_dwordx4 v[170:171], off
	v_lshl_add_u64 v[170:171], s[6:7], 0, v[144:145]
	s_add_i32 m0, s43, 0xe000
	s_nop 0
	global_load_lds_dwordx4 v[170:171], off
	s_waitcnt lgkmcnt(0)
	v_mfma_f32_16x16x32_bf16 v[124:127], v[128:131], v[194:197], v[124:127]
	s_waitcnt vmcnt(8)
	s_waitcnt lgkmcnt(0)
	s_barrier
	v_mfma_f32_16x16x32_bf16 v[116:119], v[152:155], v[194:197], v[116:119]
	v_mfma_f32_16x16x32_bf16 v[108:111], v[128:131], v[202:205], v[108:111]
	v_mfma_f32_16x16x32_bf16 v[100:103], v[152:155], v[202:205], v[100:103]
	v_mfma_f32_16x16x32_bf16 v[92:95], v[128:131], v[210:213], v[92:95]
	v_mfma_f32_16x16x32_bf16 v[84:87], v[152:155], v[210:213], v[84:87]
	v_mfma_f32_16x16x32_bf16 v[76:79], v[128:131], v[218:221], v[76:79]
	v_mfma_f32_16x16x32_bf16 v[68:71], v[152:155], v[218:221], v[68:71]
	v_mfma_f32_16x16x32_bf16 v[120:123], v[164:167], v[194:197], v[120:123]
	v_mfma_f32_16x16x32_bf16 v[112:115], v[186:189], v[194:197], v[112:115]
	v_mfma_f32_16x16x32_bf16 v[104:107], v[164:167], v[202:205], v[104:107]
	v_mfma_f32_16x16x32_bf16 v[96:99], v[186:189], v[202:205], v[96:99]
	v_mfma_f32_16x16x32_bf16 v[88:91], v[164:167], v[210:213], v[88:91]
	v_mfma_f32_16x16x32_bf16 v[80:83], v[186:189], v[210:213], v[80:83]
	v_mfma_f32_16x16x32_bf16 v[72:75], v[164:167], v[218:221], v[72:75]
	v_mfma_f32_16x16x32_bf16 v[64:67], v[186:189], v[218:221], v[64:67]
	v_mfma_f32_16x16x32_bf16 v[124:127], v[132:135], v[198:201], v[124:127]
	v_mfma_f32_16x16x32_bf16 v[116:119], v[158:161], v[198:201], v[116:119]
	v_mfma_f32_16x16x32_bf16 v[108:111], v[132:135], v[206:209], v[108:111]
	v_mfma_f32_16x16x32_bf16 v[100:103], v[158:161], v[206:209], v[100:103]
	v_mfma_f32_16x16x32_bf16 v[92:95], v[132:135], v[214:217], v[92:95]
	v_mfma_f32_16x16x32_bf16 v[84:87], v[158:161], v[214:217], v[84:87]
	v_mfma_f32_16x16x32_bf16 v[76:79], v[132:135], v[222:225], v[76:79]
	v_mfma_f32_16x16x32_bf16 v[68:71], v[158:161], v[222:225], v[68:71]
	v_mfma_f32_16x16x32_bf16 v[120:123], v[180:183], v[198:201], v[120:123]
	v_mfma_f32_16x16x32_bf16 v[112:115], v[190:193], v[198:201], v[112:115]
	v_mfma_f32_16x16x32_bf16 v[104:107], v[180:183], v[206:209], v[104:107]
	v_mfma_f32_16x16x32_bf16 v[96:99], v[190:193], v[206:209], v[96:99]
	v_mfma_f32_16x16x32_bf16 v[88:91], v[180:183], v[214:217], v[88:91]
	v_mfma_f32_16x16x32_bf16 v[80:83], v[190:193], v[214:217], v[80:83]
	v_mfma_f32_16x16x32_bf16 v[72:75], v[180:183], v[222:225], v[72:75]
	v_mfma_f32_16x16x32_bf16 v[64:67], v[190:193], v[222:225], v[64:67]
	s_barrier
	s_add_i32 s65, s56, s40
	v_lshl_add_u64 v[170:171], s[34:35], 0, v[140:141]
	s_mov_b32 m0, s65
	ds_read_b128 v[194:197], v179 offset:16384
	ds_read_b128 v[198:201], v179 offset:17408
	ds_read_b128 v[202:205], v179 offset:18432
	ds_read_b128 v[206:209], v179 offset:19456
	ds_read_b128 v[210:213], v179 offset:20480
	ds_read_b128 v[214:217], v179 offset:21504
	ds_read_b128 v[218:221], v179 offset:22528
	ds_read_b128 v[222:225], v179 offset:23552
	global_load_lds_dwordx4 v[170:171], off
	s_add_i32 m0, s65, 0x2000
	s_add_u32 s66, s34, 0x40000
	v_lshl_add_u64 v[174:175], s[34:35], 0, v[136:137]
	s_addc_u32 s67, s35, 0
	s_add_i32 s65, s57, s40
	global_load_lds_dwordx4 v[174:175], off
	v_lshl_add_u64 v[226:227], s[66:67], 0, v[140:141]
	s_mov_b32 m0, s65
	v_lshl_add_u64 v[228:229], s[36:37], 0, v[138:139]
	global_load_lds_dwordx4 v[226:227], off
	v_lshl_add_u64 v[226:227], s[66:67], 0, v[136:137]
	s_add_i32 m0, s65, 0x2000
	s_nop 0
	global_load_lds_dwordx4 v[226:227], off
	v_lshl_add_u64 v[226:227], s[36:37], 0, v[142:143]
	s_mov_b32 m0, s43
	s_nop 0
	global_load_lds_dwordx4 v[226:227], off
	s_mov_b32 m0, s44
	s_nop 0
	global_load_lds_dwordx4 v[228:229], off
	s_waitcnt lgkmcnt(0)
	v_mfma_f32_16x16x32_bf16 v[60:63], v[128:131], v[194:197], v[60:63]
	s_waitcnt vmcnt(8)
	s_waitcnt lgkmcnt(0)
	s_barrier
	v_mfma_f32_16x16x32_bf16 v[52:55], v[152:155], v[194:197], v[52:55]
	v_mfma_f32_16x16x32_bf16 v[44:47], v[128:131], v[202:205], v[44:47]
	v_mfma_f32_16x16x32_bf16 v[36:39], v[152:155], v[202:205], v[36:39]
	v_mfma_f32_16x16x32_bf16 v[28:31], v[128:131], v[210:213], v[28:31]
	v_mfma_f32_16x16x32_bf16 v[20:23], v[152:155], v[210:213], v[20:23]
	v_mfma_f32_16x16x32_bf16 v[12:15], v[128:131], v[218:221], v[12:15]
	v_mfma_f32_16x16x32_bf16 v[4:7], v[152:155], v[218:221], v[4:7]
	v_mfma_f32_16x16x32_bf16 v[56:59], v[164:167], v[194:197], v[56:59]
	v_mfma_f32_16x16x32_bf16 v[48:51], v[186:189], v[194:197], v[48:51]
	v_mfma_f32_16x16x32_bf16 v[40:43], v[164:167], v[202:205], v[40:43]
	v_mfma_f32_16x16x32_bf16 v[32:35], v[186:189], v[202:205], v[32:35]
	v_mfma_f32_16x16x32_bf16 v[24:27], v[164:167], v[210:213], v[24:27]
	v_mfma_f32_16x16x32_bf16 v[16:19], v[186:189], v[210:213], v[16:19]
	v_mfma_f32_16x16x32_bf16 v[8:11], v[164:167], v[218:221], v[8:11]
	v_mfma_f32_16x16x32_bf16 v[0:3], v[186:189], v[218:221], v[0:3]
	v_mfma_f32_16x16x32_bf16 v[60:63], v[132:135], v[198:201], v[60:63]
	v_mfma_f32_16x16x32_bf16 v[52:55], v[158:161], v[198:201], v[52:55]
	v_mfma_f32_16x16x32_bf16 v[44:47], v[132:135], v[206:209], v[44:47]
	v_mfma_f32_16x16x32_bf16 v[36:39], v[158:161], v[206:209], v[36:39]
	v_mfma_f32_16x16x32_bf16 v[28:31], v[132:135], v[214:217], v[28:31]
	v_mfma_f32_16x16x32_bf16 v[20:23], v[158:161], v[214:217], v[20:23]
	v_mfma_f32_16x16x32_bf16 v[12:15], v[132:135], v[222:225], v[12:15]
	v_mfma_f32_16x16x32_bf16 v[4:7], v[158:161], v[222:225], v[4:7]
	v_mfma_f32_16x16x32_bf16 v[56:59], v[180:183], v[198:201], v[56:59]
	v_mfma_f32_16x16x32_bf16 v[48:51], v[190:193], v[198:201], v[48:51]
	v_mfma_f32_16x16x32_bf16 v[40:43], v[180:183], v[206:209], v[40:43]
	v_mfma_f32_16x16x32_bf16 v[32:35], v[190:193], v[206:209], v[32:35]
	v_mfma_f32_16x16x32_bf16 v[24:27], v[180:183], v[214:217], v[24:27]
	v_mfma_f32_16x16x32_bf16 v[16:19], v[190:193], v[214:217], v[16:19]
	v_mfma_f32_16x16x32_bf16 v[8:11], v[180:183], v[222:225], v[8:11]
	v_mfma_f32_16x16x32_bf16 v[0:3], v[190:193], v[222:225], v[0:3]
	s_barrier
	s_add_i32 s65, 0, 0x18000
	v_add_u32_e32 v156, s65, v169
	s_add_i32 s66, 0, 0x1c000
	ds_read_b128 v[128:131], v156
	ds_read_b128 v[132:135], v156 offset:1024
	ds_read_b128 v[152:155], v156 offset:2048
	ds_read_b128 v[158:161], v156 offset:3072
	v_add_u32_e32 v156, s66, v169
	ds_read_b128 v[164:167], v156
	ds_read_b128 v[180:183], v156 offset:1024
	ds_read_b128 v[186:189], v156 offset:2048
	ds_read_b128 v[190:193], v156 offset:3072
	s_add_u32 s36, s36, 0x40000
	s_addc_u32 s37, s37, 0
	s_mov_b32 m0, s45
	v_lshl_add_u64 v[230:231], s[36:37], 0, v[142:143]
	ds_read_b128 v[194:197], v179 offset:32768
	ds_read_b128 v[198:201], v179 offset:33792
	ds_read_b128 v[202:205], v179 offset:34816
	ds_read_b128 v[206:209], v179 offset:35840
	ds_read_b128 v[210:213], v179 offset:36864
	ds_read_b128 v[214:217], v179 offset:37888
	ds_read_b128 v[218:221], v179 offset:38912
	ds_read_b128 v[222:225], v179 offset:39936
	global_load_lds_dwordx4 v[230:231], off
	v_lshl_add_u64 v[230:231], s[36:37], 0, v[138:139]
	s_mov_b32 m0, s46
	s_nop 0
	global_load_lds_dwordx4 v[230:231], off
	s_waitcnt lgkmcnt(0)
	v_mfma_f32_16x16x32_bf16 v[124:127], v[128:131], v[194:197], v[124:127]
	s_waitcnt vmcnt(8)
	s_waitcnt lgkmcnt(0)
	s_barrier
	v_mfma_f32_16x16x32_bf16 v[116:119], v[152:155], v[194:197], v[116:119]
	v_mfma_f32_16x16x32_bf16 v[108:111], v[128:131], v[202:205], v[108:111]
	v_mfma_f32_16x16x32_bf16 v[100:103], v[152:155], v[202:205], v[100:103]
	v_mfma_f32_16x16x32_bf16 v[92:95], v[128:131], v[210:213], v[92:95]
	v_mfma_f32_16x16x32_bf16 v[84:87], v[152:155], v[210:213], v[84:87]
	v_mfma_f32_16x16x32_bf16 v[76:79], v[128:131], v[218:221], v[76:79]
	v_mfma_f32_16x16x32_bf16 v[68:71], v[152:155], v[218:221], v[68:71]
	v_mfma_f32_16x16x32_bf16 v[120:123], v[164:167], v[194:197], v[120:123]
	v_mfma_f32_16x16x32_bf16 v[112:115], v[186:189], v[194:197], v[112:115]
	v_mfma_f32_16x16x32_bf16 v[104:107], v[164:167], v[202:205], v[104:107]
	v_mfma_f32_16x16x32_bf16 v[96:99], v[186:189], v[202:205], v[96:99]
	v_mfma_f32_16x16x32_bf16 v[88:91], v[164:167], v[210:213], v[88:91]
	v_mfma_f32_16x16x32_bf16 v[80:83], v[186:189], v[210:213], v[80:83]
	v_mfma_f32_16x16x32_bf16 v[72:75], v[164:167], v[218:221], v[72:75]
	v_mfma_f32_16x16x32_bf16 v[64:67], v[186:189], v[218:221], v[64:67]
	v_mfma_f32_16x16x32_bf16 v[124:127], v[132:135], v[198:201], v[124:127]
	v_mfma_f32_16x16x32_bf16 v[116:119], v[158:161], v[198:201], v[116:119]
	v_mfma_f32_16x16x32_bf16 v[108:111], v[132:135], v[206:209], v[108:111]
	v_mfma_f32_16x16x32_bf16 v[100:103], v[158:161], v[206:209], v[100:103]
	v_mfma_f32_16x16x32_bf16 v[92:95], v[132:135], v[214:217], v[92:95]
	v_mfma_f32_16x16x32_bf16 v[84:87], v[158:161], v[214:217], v[84:87]
	v_mfma_f32_16x16x32_bf16 v[76:79], v[132:135], v[222:225], v[76:79]
	v_mfma_f32_16x16x32_bf16 v[68:71], v[158:161], v[222:225], v[68:71]
	v_mfma_f32_16x16x32_bf16 v[120:123], v[180:183], v[198:201], v[120:123]
	v_mfma_f32_16x16x32_bf16 v[112:115], v[190:193], v[198:201], v[112:115]
	v_mfma_f32_16x16x32_bf16 v[104:107], v[180:183], v[206:209], v[104:107]
	v_mfma_f32_16x16x32_bf16 v[96:99], v[190:193], v[206:209], v[96:99]
	v_mfma_f32_16x16x32_bf16 v[88:91], v[180:183], v[214:217], v[88:91]
	v_mfma_f32_16x16x32_bf16 v[80:83], v[190:193], v[214:217], v[80:83]
	v_mfma_f32_16x16x32_bf16 v[72:75], v[180:183], v[222:225], v[72:75]
	v_mfma_f32_16x16x32_bf16 v[64:67], v[190:193], v[222:225], v[64:67]
	s_barrier
	s_add_i32 s36, s65, s40
	v_lshl_add_u64 v[170:171], v[170:171], 0, s[14:15]
	s_mov_b32 m0, s36
	ds_read_b128 v[194:197], v179 offset:49152
	ds_read_b128 v[198:201], v179 offset:50176
	ds_read_b128 v[202:205], v179 offset:51200
	ds_read_b128 v[206:209], v179 offset:52224
	ds_read_b128 v[210:213], v179 offset:53248
	ds_read_b128 v[214:217], v179 offset:54272
	ds_read_b128 v[218:221], v179 offset:55296
	ds_read_b128 v[222:225], v179 offset:56320
	global_load_lds_dwordx4 v[170:171], off
	s_add_i32 m0, s36, 0x2000
	s_add_u32 s34, s34, 0x40080
	v_lshl_add_u64 v[170:171], v[174:175], 0, s[14:15]
	s_addc_u32 s35, s35, 0
	s_add_i32 s36, s66, s40
	global_load_lds_dwordx4 v[170:171], off
	v_lshl_add_u64 v[170:171], s[34:35], 0, v[140:141]
	s_mov_b32 m0, s36
	s_nop 0
	global_load_lds_dwordx4 v[170:171], off
	v_lshl_add_u64 v[170:171], s[34:35], 0, v[136:137]
	s_add_i32 m0, s36, 0x2000
	s_nop 0
	global_load_lds_dwordx4 v[170:171], off
	v_lshl_add_u64 v[170:171], v[226:227], 0, s[14:15]
	s_mov_b32 m0, s53
	s_nop 0
	global_load_lds_dwordx4 v[170:171], off
	v_lshl_add_u64 v[170:171], v[228:229], 0, s[14:15]
	s_mov_b32 m0, s54
	s_nop 0
	global_load_lds_dwordx4 v[170:171], off
	s_waitcnt lgkmcnt(0)
	v_mfma_f32_16x16x32_bf16 v[60:63], v[128:131], v[194:197], v[60:63]
	s_waitcnt vmcnt(8)
	s_waitcnt lgkmcnt(0)
	s_barrier
	v_mfma_f32_16x16x32_bf16 v[52:55], v[152:155], v[194:197], v[52:55]
	v_mfma_f32_16x16x32_bf16 v[44:47], v[128:131], v[202:205], v[44:47]
	v_mfma_f32_16x16x32_bf16 v[36:39], v[152:155], v[202:205], v[36:39]
	v_mfma_f32_16x16x32_bf16 v[28:31], v[128:131], v[210:213], v[28:31]
	v_mfma_f32_16x16x32_bf16 v[20:23], v[152:155], v[210:213], v[20:23]
	v_mfma_f32_16x16x32_bf16 v[12:15], v[128:131], v[218:221], v[12:15]
	v_mfma_f32_16x16x32_bf16 v[4:7], v[152:155], v[218:221], v[4:7]
	v_mfma_f32_16x16x32_bf16 v[56:59], v[164:167], v[194:197], v[56:59]
	v_mfma_f32_16x16x32_bf16 v[48:51], v[186:189], v[194:197], v[48:51]
	v_mfma_f32_16x16x32_bf16 v[40:43], v[164:167], v[202:205], v[40:43]
	v_mfma_f32_16x16x32_bf16 v[32:35], v[186:189], v[202:205], v[32:35]
	v_mfma_f32_16x16x32_bf16 v[24:27], v[164:167], v[210:213], v[24:27]
	v_mfma_f32_16x16x32_bf16 v[16:19], v[186:189], v[210:213], v[16:19]
	v_mfma_f32_16x16x32_bf16 v[8:11], v[164:167], v[218:221], v[8:11]
	v_mfma_f32_16x16x32_bf16 v[0:3], v[186:189], v[218:221], v[0:3]
	v_mfma_f32_16x16x32_bf16 v[60:63], v[132:135], v[198:201], v[60:63]
	v_mfma_f32_16x16x32_bf16 v[52:55], v[158:161], v[198:201], v[52:55]
	v_mfma_f32_16x16x32_bf16 v[44:47], v[132:135], v[206:209], v[44:47]
	v_mfma_f32_16x16x32_bf16 v[36:39], v[158:161], v[206:209], v[36:39]
	v_mfma_f32_16x16x32_bf16 v[28:31], v[132:135], v[214:217], v[28:31]
	v_mfma_f32_16x16x32_bf16 v[20:23], v[158:161], v[214:217], v[20:23]
	v_mfma_f32_16x16x32_bf16 v[12:15], v[132:135], v[222:225], v[12:15]
	v_mfma_f32_16x16x32_bf16 v[4:7], v[158:161], v[222:225], v[4:7]
	v_mfma_f32_16x16x32_bf16 v[56:59], v[180:183], v[198:201], v[56:59]
	v_mfma_f32_16x16x32_bf16 v[48:51], v[190:193], v[198:201], v[48:51]
	v_mfma_f32_16x16x32_bf16 v[40:43], v[180:183], v[206:209], v[40:43]
	v_mfma_f32_16x16x32_bf16 v[32:35], v[190:193], v[206:209], v[32:35]
	v_mfma_f32_16x16x32_bf16 v[24:27], v[180:183], v[214:217], v[24:27]
	v_mfma_f32_16x16x32_bf16 v[16:19], v[190:193], v[214:217], v[16:19]
	v_mfma_f32_16x16x32_bf16 v[8:11], v[180:183], v[222:225], v[8:11]
	v_mfma_f32_16x16x32_bf16 v[0:3], v[190:193], v[222:225], v[0:3]
	s_barrier
	s_add_i32 s64, s64, 2
	s_add_u32 s62, s62, 0x100
	s_addc_u32 s63, s63, 0
	s_add_u32 s6, s6, 0x100
	s_addc_u32 s7, s7, 0
	s_cmp_gt_u32 s64, 13
	s_cbranch_scc0 .LBB0_930
	s_and_b64 vcc, exec, s[16:17]
	s_cbranch_vccz .LBB0_933
	s_barrier

.LBB0_1002:
	ds_read_b128 v[144:147], v171
	ds_read_b128 v[148:151], v171 offset:1024
	ds_read_b128 v[152:155], v171 offset:2048
	ds_read_b128 v[156:159], v171 offset:3072
	ds_read_b128 v[160:163], v172
	ds_read_b128 v[164:167], v172 offset:1024
	ds_read_b128 v[174:177], v172 offset:2048
	ds_read_b128 v[178:181], v172 offset:3072
	s_add_u32 s16, s14, 0x100
	s_addc_u32 s17, s15, 0
	s_cmp_eq_u32 s50, 40
	s_cselect_b32 s21, s3, s17
	s_cselect_b32 s20, s2, s16
	s_cselect_b32 s19, s13, s49
	s_cselect_b32 s18, s12, s48
	v_lshl_add_u64 v[214:215], s[14:15], 0, v[138:139]
	s_add_i32 m0, s28, 0xc000
	ds_read_b128 v[182:185], v173
	ds_read_b128 v[186:189], v173 offset:1024
	ds_read_b128 v[190:193], v173 offset:2048
	ds_read_b128 v[194:197], v173 offset:3072
	ds_read_b128 v[198:201], v173 offset:4096
	ds_read_b128 v[202:205], v173 offset:5120
	ds_read_b128 v[206:209], v173 offset:6144
	ds_read_b128 v[210:213], v173 offset:7168
	global_load_lds_dwordx4 v[214:215], off
	v_lshl_add_u64 v[214:215], s[14:15], 0, v[136:137]
	s_add_i32 m0, s28, 0xe000
	s_nop 0
	global_load_lds_dwordx4 v[214:215], off
	s_waitcnt lgkmcnt(0)
	v_mfma_f32_16x16x32_bf16 v[124:127], v[144:147], v[182:185], v[124:127]
	s_waitcnt vmcnt(8)
	s_waitcnt lgkmcnt(0)
	s_barrier
	v_mfma_f32_16x16x32_bf16 v[120:123], v[152:155], v[182:185], v[120:123]
	v_mfma_f32_16x16x32_bf16 v[116:119], v[144:147], v[190:193], v[116:119]
	v_mfma_f32_16x16x32_bf16 v[112:115], v[152:155], v[190:193], v[112:115]
	v_mfma_f32_16x16x32_bf16 v[108:111], v[144:147], v[198:201], v[108:111]
	v_mfma_f32_16x16x32_bf16 v[104:107], v[152:155], v[198:201], v[104:107]
	v_mfma_f32_16x16x32_bf16 v[100:103], v[144:147], v[206:209], v[100:103]
	v_mfma_f32_16x16x32_bf16 v[96:99], v[152:155], v[206:209], v[96:99]
	v_mfma_f32_16x16x32_bf16 v[60:63], v[160:163], v[182:185], v[60:63]
	v_mfma_f32_16x16x32_bf16 v[56:59], v[174:177], v[182:185], v[56:59]
	v_mfma_f32_16x16x32_bf16 v[52:55], v[160:163], v[190:193], v[52:55]
	v_mfma_f32_16x16x32_bf16 v[48:51], v[174:177], v[190:193], v[48:51]
	v_mfma_f32_16x16x32_bf16 v[44:47], v[160:163], v[198:201], v[44:47]
	v_mfma_f32_16x16x32_bf16 v[40:43], v[174:177], v[198:201], v[40:43]
	v_mfma_f32_16x16x32_bf16 v[36:39], v[160:163], v[206:209], v[36:39]
	v_mfma_f32_16x16x32_bf16 v[32:35], v[174:177], v[206:209], v[32:35]
	v_mfma_f32_16x16x32_bf16 v[124:127], v[148:151], v[186:189], v[124:127]
	v_mfma_f32_16x16x32_bf16 v[120:123], v[156:159], v[186:189], v[120:123]
	v_mfma_f32_16x16x32_bf16 v[116:119], v[148:151], v[194:197], v[116:119]
	v_mfma_f32_16x16x32_bf16 v[112:115], v[156:159], v[194:197], v[112:115]
	v_mfma_f32_16x16x32_bf16 v[108:111], v[148:151], v[202:205], v[108:111]
	v_mfma_f32_16x16x32_bf16 v[104:107], v[156:159], v[202:205], v[104:107]
	v_mfma_f32_16x16x32_bf16 v[100:103], v[148:151], v[210:213], v[100:103]
	v_mfma_f32_16x16x32_bf16 v[96:99], v[156:159], v[210:213], v[96:99]
	v_mfma_f32_16x16x32_bf16 v[60:63], v[164:167], v[186:189], v[60:63]
	v_mfma_f32_16x16x32_bf16 v[56:59], v[178:181], v[186:189], v[56:59]
	v_mfma_f32_16x16x32_bf16 v[52:55], v[164:167], v[194:197], v[52:55]
	v_mfma_f32_16x16x32_bf16 v[48:51], v[178:181], v[194:197], v[48:51]
	v_mfma_f32_16x16x32_bf16 v[44:47], v[164:167], v[202:205], v[44:47]
	v_mfma_f32_16x16x32_bf16 v[40:43], v[178:181], v[202:205], v[40:43]
	v_mfma_f32_16x16x32_bf16 v[36:39], v[164:167], v[210:213], v[36:39]
	v_mfma_f32_16x16x32_bf16 v[32:35], v[178:181], v[210:213], v[32:35]
	s_barrier
	s_add_i32 s14, s42, s27
	v_lshl_add_u64 v[214:215], s[18:19], 0, v[130:131]
	s_mov_b32 m0, s14
	ds_read_b128 v[182:185], v173 offset:16384
	ds_read_b128 v[186:189], v173 offset:17408
	ds_read_b128 v[190:193], v173 offset:18432
	ds_read_b128 v[194:197], v173 offset:19456
	ds_read_b128 v[198:201], v173 offset:20480
	ds_read_b128 v[202:205], v173 offset:21504
	ds_read_b128 v[206:209], v173 offset:22528
	ds_read_b128 v[210:213], v173 offset:23552
	global_load_lds_dwordx4 v[214:215], off
	s_add_i32 m0, s14, 0x2000
	s_add_u32 s14, s18, 0xb0000
	v_lshl_add_u64 v[216:217], s[18:19], 0, v[134:135]
	s_addc_u32 s15, s19, 0
	s_add_i32 s51, s43, s27
	global_load_lds_dwordx4 v[216:217], off
	v_lshl_add_u64 v[218:219], s[14:15], 0, v[130:131]
	s_mov_b32 m0, s51
	v_lshl_add_u64 v[220:221], s[20:21], 0, v[132:133]
	global_load_lds_dwordx4 v[218:219], off
	v_lshl_add_u64 v[218:219], s[14:15], 0, v[134:135]
	s_add_i32 m0, s51, 0x2000
	s_nop 0
	global_load_lds_dwordx4 v[218:219], off
	v_lshl_add_u64 v[218:219], s[20:21], 0, v[128:129]
	s_mov_b32 m0, s28
	s_nop 0
	global_load_lds_dwordx4 v[218:219], off
	s_mov_b32 m0, s29
	s_nop 0
	global_load_lds_dwordx4 v[220:221], off
	s_waitcnt lgkmcnt(0)
	v_mfma_f32_16x16x32_bf16 v[92:95], v[144:147], v[182:185], v[92:95]
	s_waitcnt vmcnt(8)
	s_waitcnt lgkmcnt(0)
	s_barrier
	v_mfma_f32_16x16x32_bf16 v[88:91], v[152:155], v[182:185], v[88:91]
	v_mfma_f32_16x16x32_bf16 v[84:87], v[144:147], v[190:193], v[84:87]
	v_mfma_f32_16x16x32_bf16 v[80:83], v[152:155], v[190:193], v[80:83]
	v_mfma_f32_16x16x32_bf16 v[76:79], v[144:147], v[198:201], v[76:79]
	v_mfma_f32_16x16x32_bf16 v[72:75], v[152:155], v[198:201], v[72:75]
	v_mfma_f32_16x16x32_bf16 v[68:71], v[144:147], v[206:209], v[68:71]
	v_mfma_f32_16x16x32_bf16 v[64:67], v[152:155], v[206:209], v[64:67]
	v_mfma_f32_16x16x32_bf16 v[28:31], v[160:163], v[182:185], v[28:31]
	v_mfma_f32_16x16x32_bf16 v[24:27], v[174:177], v[182:185], v[24:27]
	v_mfma_f32_16x16x32_bf16 v[20:23], v[160:163], v[190:193], v[20:23]
	v_mfma_f32_16x16x32_bf16 v[16:19], v[174:177], v[190:193], v[16:19]
	v_mfma_f32_16x16x32_bf16 v[12:15], v[160:163], v[198:201], v[12:15]
	v_mfma_f32_16x16x32_bf16 v[8:11], v[174:177], v[198:201], v[8:11]
	v_mfma_f32_16x16x32_bf16 v[4:7], v[160:163], v[206:209], v[4:7]
	v_mfma_f32_16x16x32_bf16 v[0:3], v[174:177], v[206:209], v[0:3]
	v_mfma_f32_16x16x32_bf16 v[92:95], v[148:151], v[186:189], v[92:95]
	v_mfma_f32_16x16x32_bf16 v[88:91], v[156:159], v[186:189], v[88:91]
	v_mfma_f32_16x16x32_bf16 v[84:87], v[148:151], v[194:197], v[84:87]
	v_mfma_f32_16x16x32_bf16 v[80:83], v[156:159], v[194:197], v[80:83]
	v_mfma_f32_16x16x32_bf16 v[76:79], v[148:151], v[202:205], v[76:79]
	v_mfma_f32_16x16x32_bf16 v[72:75], v[156:159], v[202:205], v[72:75]
	v_mfma_f32_16x16x32_bf16 v[68:71], v[148:151], v[210:213], v[68:71]
	v_mfma_f32_16x16x32_bf16 v[64:67], v[156:159], v[210:213], v[64:67]
	v_mfma_f32_16x16x32_bf16 v[28:31], v[164:167], v[186:189], v[28:31]
	v_mfma_f32_16x16x32_bf16 v[24:27], v[178:181], v[186:189], v[24:27]
	v_mfma_f32_16x16x32_bf16 v[20:23], v[164:167], v[194:197], v[20:23]
	v_mfma_f32_16x16x32_bf16 v[16:19], v[178:181], v[194:197], v[16:19]
	v_mfma_f32_16x16x32_bf16 v[12:15], v[164:167], v[202:205], v[12:15]
	v_mfma_f32_16x16x32_bf16 v[8:11], v[178:181], v[202:205], v[8:11]
	v_mfma_f32_16x16x32_bf16 v[4:7], v[164:167], v[210:213], v[4:7]
	v_mfma_f32_16x16x32_bf16 v[0:3], v[178:181], v[210:213], v[0:3]
	s_barrier
	s_add_i32 s51, 0, 0x18000
	s_add_i32 s52, 0, 0x1c000
	v_add_u32_e32 v156, s51, v170
	v_add_u32_e32 v178, s52, v170
	ds_read_b128 v[144:147], v156
	ds_read_b128 v[148:151], v156 offset:1024
	ds_read_b128 v[152:155], v156 offset:2048
	ds_read_b128 v[156:159], v156 offset:3072
	ds_read_b128 v[160:163], v178
	ds_read_b128 v[164:167], v178 offset:1024
	ds_read_b128 v[174:177], v178 offset:2048
	ds_read_b128 v[178:181], v178 offset:3072
	s_add_u32 s14, s20, 0xb0000
	s_addc_u32 s15, s21, 0
	s_mov_b32 m0, s30
	v_lshl_add_u64 v[222:223], s[14:15], 0, v[128:129]
	ds_read_b128 v[182:185], v173 offset:32768
	ds_read_b128 v[186:189], v173 offset:33792
	ds_read_b128 v[190:193], v173 offset:34816
	ds_read_b128 v[194:197], v173 offset:35840
	ds_read_b128 v[198:201], v173 offset:36864
	ds_read_b128 v[202:205], v173 offset:37888
	ds_read_b128 v[206:209], v173 offset:38912
	ds_read_b128 v[210:213], v173 offset:39936
	global_load_lds_dwordx4 v[222:223], off
	v_lshl_add_u64 v[222:223], s[14:15], 0, v[132:133]
	s_mov_b32 m0, s31
	s_nop 0
	global_load_lds_dwordx4 v[222:223], off
	s_waitcnt lgkmcnt(0)
	v_mfma_f32_16x16x32_bf16 v[124:127], v[144:147], v[182:185], v[124:127]
	s_waitcnt vmcnt(8)
	s_waitcnt lgkmcnt(0)
	s_barrier
	v_mfma_f32_16x16x32_bf16 v[120:123], v[152:155], v[182:185], v[120:123]
	v_mfma_f32_16x16x32_bf16 v[116:119], v[144:147], v[190:193], v[116:119]
	v_mfma_f32_16x16x32_bf16 v[112:115], v[152:155], v[190:193], v[112:115]
	v_mfma_f32_16x16x32_bf16 v[108:111], v[144:147], v[198:201], v[108:111]
	v_mfma_f32_16x16x32_bf16 v[104:107], v[152:155], v[198:201], v[104:107]
	v_mfma_f32_16x16x32_bf16 v[100:103], v[144:147], v[206:209], v[100:103]
	v_mfma_f32_16x16x32_bf16 v[96:99], v[152:155], v[206:209], v[96:99]
	v_mfma_f32_16x16x32_bf16 v[60:63], v[160:163], v[182:185], v[60:63]
	v_mfma_f32_16x16x32_bf16 v[56:59], v[174:177], v[182:185], v[56:59]
	v_mfma_f32_16x16x32_bf16 v[52:55], v[160:163], v[190:193], v[52:55]
	v_mfma_f32_16x16x32_bf16 v[48:51], v[174:177], v[190:193], v[48:51]
	v_mfma_f32_16x16x32_bf16 v[44:47], v[160:163], v[198:201], v[44:47]
	v_mfma_f32_16x16x32_bf16 v[40:43], v[174:177], v[198:201], v[40:43]
	v_mfma_f32_16x16x32_bf16 v[36:39], v[160:163], v[206:209], v[36:39]
	v_mfma_f32_16x16x32_bf16 v[32:35], v[174:177], v[206:209], v[32:35]
	v_mfma_f32_16x16x32_bf16 v[124:127], v[148:151], v[186:189], v[124:127]
	v_mfma_f32_16x16x32_bf16 v[120:123], v[156:159], v[186:189], v[120:123]
	v_mfma_f32_16x16x32_bf16 v[116:119], v[148:151], v[194:197], v[116:119]
	v_mfma_f32_16x16x32_bf16 v[112:115], v[156:159], v[194:197], v[112:115]
	v_mfma_f32_16x16x32_bf16 v[108:111], v[148:151], v[202:205], v[108:111]
	v_mfma_f32_16x16x32_bf16 v[104:107], v[156:159], v[202:205], v[104:107]
	v_mfma_f32_16x16x32_bf16 v[100:103], v[148:151], v[210:213], v[100:103]
	v_mfma_f32_16x16x32_bf16 v[96:99], v[156:159], v[210:213], v[96:99]
	v_mfma_f32_16x16x32_bf16 v[60:63], v[164:167], v[186:189], v[60:63]
	v_mfma_f32_16x16x32_bf16 v[56:59], v[178:181], v[186:189], v[56:59]
	v_mfma_f32_16x16x32_bf16 v[52:55], v[164:167], v[194:197], v[52:55]
	v_mfma_f32_16x16x32_bf16 v[48:51], v[178:181], v[194:197], v[48:51]
	v_mfma_f32_16x16x32_bf16 v[44:47], v[164:167], v[202:205], v[44:47]
	v_mfma_f32_16x16x32_bf16 v[40:43], v[178:181], v[202:205], v[40:43]
	v_mfma_f32_16x16x32_bf16 v[36:39], v[164:167], v[210:213], v[36:39]
	v_mfma_f32_16x16x32_bf16 v[32:35], v[178:181], v[210:213], v[32:35]
	s_barrier
	s_add_i32 s14, s51, s27
	v_lshl_add_u64 v[214:215], v[214:215], 0, s[8:9]
	s_mov_b32 m0, s14
	ds_read_b128 v[182:185], v173 offset:49152
	ds_read_b128 v[186:189], v173 offset:50176
	ds_read_b128 v[190:193], v173 offset:51200
	ds_read_b128 v[194:197], v173 offset:52224
	ds_read_b128 v[198:201], v173 offset:53248
	ds_read_b128 v[202:205], v173 offset:54272
	ds_read_b128 v[206:209], v173 offset:55296
	ds_read_b128 v[210:213], v173 offset:56320
	global_load_lds_dwordx4 v[214:215], off
	s_add_i32 m0, s14, 0x2000
	s_add_u32 s14, s18, 0xb0080
	v_lshl_add_u64 v[214:215], v[216:217], 0, s[8:9]
	s_addc_u32 s15, s19, 0
	s_add_i32 s18, s52, s27
	global_load_lds_dwordx4 v[214:215], off
	v_lshl_add_u64 v[214:215], s[14:15], 0, v[130:131]
	s_mov_b32 m0, s18
	s_nop 0
	global_load_lds_dwordx4 v[214:215], off
	v_lshl_add_u64 v[214:215], s[14:15], 0, v[134:135]
	s_add_i32 m0, s18, 0x2000
	s_nop 0
	global_load_lds_dwordx4 v[214:215], off
	v_lshl_add_u64 v[214:215], v[218:219], 0, s[8:9]
	s_mov_b32 m0, s39
	s_nop 0
	global_load_lds_dwordx4 v[214:215], off
	v_lshl_add_u64 v[214:215], v[220:221], 0, s[8:9]
	s_mov_b32 m0, s40
	s_nop 0
	global_load_lds_dwordx4 v[214:215], off
	s_waitcnt lgkmcnt(0)
	v_mfma_f32_16x16x32_bf16 v[92:95], v[144:147], v[182:185], v[92:95]
	s_waitcnt vmcnt(8)
	s_waitcnt lgkmcnt(0)
	s_barrier
	v_mfma_f32_16x16x32_bf16 v[88:91], v[152:155], v[182:185], v[88:91]
	v_mfma_f32_16x16x32_bf16 v[84:87], v[144:147], v[190:193], v[84:87]
	v_mfma_f32_16x16x32_bf16 v[80:83], v[152:155], v[190:193], v[80:83]
	v_mfma_f32_16x16x32_bf16 v[76:79], v[144:147], v[198:201], v[76:79]
	v_mfma_f32_16x16x32_bf16 v[72:75], v[152:155], v[198:201], v[72:75]
	v_mfma_f32_16x16x32_bf16 v[68:71], v[144:147], v[206:209], v[68:71]
	v_mfma_f32_16x16x32_bf16 v[64:67], v[152:155], v[206:209], v[64:67]
	v_mfma_f32_16x16x32_bf16 v[28:31], v[160:163], v[182:185], v[28:31]
	v_mfma_f32_16x16x32_bf16 v[24:27], v[174:177], v[182:185], v[24:27]
	v_mfma_f32_16x16x32_bf16 v[20:23], v[160:163], v[190:193], v[20:23]
	v_mfma_f32_16x16x32_bf16 v[16:19], v[174:177], v[190:193], v[16:19]
	v_mfma_f32_16x16x32_bf16 v[12:15], v[160:163], v[198:201], v[12:15]
	v_mfma_f32_16x16x32_bf16 v[8:11], v[174:177], v[198:201], v[8:11]
	v_mfma_f32_16x16x32_bf16 v[4:7], v[160:163], v[206:209], v[4:7]
	v_mfma_f32_16x16x32_bf16 v[0:3], v[174:177], v[206:209], v[0:3]
	v_mfma_f32_16x16x32_bf16 v[92:95], v[148:151], v[186:189], v[92:95]
	v_mfma_f32_16x16x32_bf16 v[88:91], v[156:159], v[186:189], v[88:91]
	v_mfma_f32_16x16x32_bf16 v[84:87], v[148:151], v[194:197], v[84:87]
	v_mfma_f32_16x16x32_bf16 v[80:83], v[156:159], v[194:197], v[80:83]
	v_mfma_f32_16x16x32_bf16 v[76:79], v[148:151], v[202:205], v[76:79]
	v_mfma_f32_16x16x32_bf16 v[72:75], v[156:159], v[202:205], v[72:75]
	v_mfma_f32_16x16x32_bf16 v[68:71], v[148:151], v[210:213], v[68:71]
	v_mfma_f32_16x16x32_bf16 v[64:67], v[156:159], v[210:213], v[64:67]
	v_mfma_f32_16x16x32_bf16 v[28:31], v[164:167], v[186:189], v[28:31]
	v_mfma_f32_16x16x32_bf16 v[24:27], v[178:181], v[186:189], v[24:27]
	v_mfma_f32_16x16x32_bf16 v[20:23], v[164:167], v[194:197], v[20:23]
	v_mfma_f32_16x16x32_bf16 v[16:19], v[178:181], v[194:197], v[16:19]
	v_mfma_f32_16x16x32_bf16 v[12:15], v[164:167], v[202:205], v[12:15]
	v_mfma_f32_16x16x32_bf16 v[8:11], v[178:181], v[202:205], v[8:11]
	v_mfma_f32_16x16x32_bf16 v[4:7], v[164:167], v[210:213], v[4:7]
	v_mfma_f32_16x16x32_bf16 v[0:3], v[178:181], v[210:213], v[0:3]
	s_barrier
	s_add_i32 s50, s50, 2
	s_add_u32 s48, s48, 0x100
	s_addc_u32 s49, s49, 0
	s_cmp_gt_u32 s50, 41
	s_mov_b64 s[14:15], s[16:17]
	s_cbranch_scc0 .LBB0_1002
	s_and_b64 vcc, exec, s[10:11]
	s_cbranch_vccz .LBB0_1005
	s_barrier
